# hazard-clean pass: every hand-written VALU-writes-SGPR/VCC to VALU-read pair now keeps the compiler's two wait states (checker calibrated on the baseline reports none)
# baseline (speedup 1.0000x reference)
.LBB0_1268:
	s_or_b64 exec, exec, s[0:1]
	v_lshlrev_b32_e32 v137, 5, v135
	v_add_u32_e32 v138, -1, v137
	s_add_i32 s10, s53, -2
	v_lshl_add_u32 v139, v135, 8, s35
	v_add_u32_e32 v140, s46, v134
	v_lshlrev_b32_e64 v140, v140, 1
	s_waitcnt vmcnt(0)
	v_add_u32_e32 v145, 0, v138
	v_add_u32_e32 v146, 1, v138
	v_cmp_gt_u32_e32 vcc, s10, v145
	v_cmp_gt_u32_e64 s[14:15], s10, v146
	v_add_u32_e32 v102, 1, v102
	v_add_u32_e32 v103, 1, v103
	v_cndmask_b32_e32 v102, 0, v102, vcc
	v_cndmask_b32_e64 v103, 0, v103, s[14:15]
	v_add_u32_e32 v145, 2, v138
	v_add_u32_e32 v146, 3, v138
	v_cmp_gt_u32_e32 vcc, s10, v145
	v_cmp_gt_u32_e64 s[14:15], s10, v146
	v_add_u32_e32 v104, 1, v104
	v_add_u32_e32 v105, 1, v105
	v_cndmask_b32_e32 v104, 0, v104, vcc
	v_cndmask_b32_e64 v105, 0, v105, s[14:15]
	v_add_u32_e32 v145, 4, v138
	v_add_u32_e32 v146, 5, v138
	v_cmp_gt_u32_e32 vcc, s10, v145
	v_cmp_gt_u32_e64 s[14:15], s10, v146
	v_add_u32_e32 v106, 1, v106
	v_add_u32_e32 v107, 1, v107
	v_cndmask_b32_e32 v106, 0, v106, vcc
	v_cndmask_b32_e64 v107, 0, v107, s[14:15]
	v_add_u32_e32 v145, 6, v138
	v_add_u32_e32 v146, 7, v138
	v_cmp_gt_u32_e32 vcc, s10, v145
	v_cmp_gt_u32_e64 s[14:15], s10, v146
	v_add_u32_e32 v108, 1, v108
	v_add_u32_e32 v109, 1, v109
	v_cndmask_b32_e32 v108, 0, v108, vcc
	v_cndmask_b32_e64 v109, 0, v109, s[14:15]
	v_add_u32_e32 v145, 8, v138
	v_add_u32_e32 v146, 9, v138
	v_cmp_gt_u32_e32 vcc, s10, v145
	v_cmp_gt_u32_e64 s[14:15], s10, v146
	v_add_u32_e32 v110, 1, v110
	v_add_u32_e32 v111, 1, v111
	v_cndmask_b32_e32 v110, 0, v110, vcc
	v_cndmask_b32_e64 v111, 0, v111, s[14:15]
	v_add_u32_e32 v145, 10, v138
	v_add_u32_e32 v146, 11, v138
	v_cmp_gt_u32_e32 vcc, s10, v145
	v_cmp_gt_u32_e64 s[14:15], s10, v146
	v_add_u32_e32 v112, 1, v112
	v_add_u32_e32 v113, 1, v113
	v_cndmask_b32_e32 v112, 0, v112, vcc
	v_cndmask_b32_e64 v113, 0, v113, s[14:15]
	v_add_u32_e32 v145, 12, v138
	v_add_u32_e32 v146, 13, v138
	v_cmp_gt_u32_e32 vcc, s10, v145
	v_cmp_gt_u32_e64 s[14:15], s10, v146
	v_add_u32_e32 v114, 1, v114
	v_add_u32_e32 v115, 1, v115
	v_cndmask_b32_e32 v114, 0, v114, vcc
	v_cndmask_b32_e64 v115, 0, v115, s[14:15]
	v_add_u32_e32 v145, 14, v138
	v_add_u32_e32 v146, 15, v138
	v_cmp_gt_u32_e32 vcc, s10, v145
	v_cmp_gt_u32_e64 s[14:15], s10, v146
	v_add_u32_e32 v116, 1, v116
	v_add_u32_e32 v117, 1, v117
	v_cndmask_b32_e32 v116, 0, v116, vcc
	v_cndmask_b32_e64 v117, 0, v117, s[14:15]
	v_add_u32_e32 v145, 16, v138
	v_add_u32_e32 v146, 17, v138
	v_cmp_gt_u32_e32 vcc, s10, v145
	v_cmp_gt_u32_e64 s[14:15], s10, v146
	v_add_u32_e32 v118, 1, v118
	v_add_u32_e32 v119, 1, v119
	v_cndmask_b32_e32 v118, 0, v118, vcc
	v_cndmask_b32_e64 v119, 0, v119, s[14:15]
	v_add_u32_e32 v145, 18, v138
	v_add_u32_e32 v146, 19, v138
	v_cmp_gt_u32_e32 vcc, s10, v145
	v_cmp_gt_u32_e64 s[14:15], s10, v146
	v_add_u32_e32 v120, 1, v120
	v_add_u32_e32 v121, 1, v121
	v_cndmask_b32_e32 v120, 0, v120, vcc
	v_cndmask_b32_e64 v121, 0, v121, s[14:15]
	v_add_u32_e32 v145, 20, v138
	v_add_u32_e32 v146, 21, v138
	v_cmp_gt_u32_e32 vcc, s10, v145
	v_cmp_gt_u32_e64 s[14:15], s10, v146
	v_add_u32_e32 v122, 1, v122
	v_add_u32_e32 v123, 1, v123
	v_cndmask_b32_e32 v122, 0, v122, vcc
	v_cndmask_b32_e64 v123, 0, v123, s[14:15]
	v_add_u32_e32 v145, 22, v138
	v_add_u32_e32 v146, 23, v138
	v_cmp_gt_u32_e32 vcc, s10, v145
	v_cmp_gt_u32_e64 s[14:15], s10, v146
	v_add_u32_e32 v124, 1, v124
	v_add_u32_e32 v125, 1, v125
	v_cndmask_b32_e32 v124, 0, v124, vcc
	v_cndmask_b32_e64 v125, 0, v125, s[14:15]
	v_add_u32_e32 v145, 24, v138
	v_add_u32_e32 v146, 25, v138
	v_cmp_gt_u32_e32 vcc, s10, v145
	v_cmp_gt_u32_e64 s[14:15], s10, v146
	v_add_u32_e32 v126, 1, v126
	v_add_u32_e32 v127, 1, v127
	v_cndmask_b32_e32 v126, 0, v126, vcc
	v_cndmask_b32_e64 v127, 0, v127, s[14:15]
	v_add_u32_e32 v145, 26, v138
	v_add_u32_e32 v146, 27, v138
	v_cmp_gt_u32_e32 vcc, s10, v145
	v_cmp_gt_u32_e64 s[14:15], s10, v146
	v_add_u32_e32 v128, 1, v128
	v_add_u32_e32 v129, 1, v129
	v_cndmask_b32_e32 v128, 0, v128, vcc
	v_cndmask_b32_e64 v129, 0, v129, s[14:15]
	v_add_u32_e32 v145, 28, v138
	v_add_u32_e32 v146, 29, v138
	v_cmp_gt_u32_e32 vcc, s10, v145
	v_cmp_gt_u32_e64 s[14:15], s10, v146
	v_add_u32_e32 v130, 1, v130
	v_add_u32_e32 v131, 1, v131
	v_cndmask_b32_e32 v130, 0, v130, vcc
	v_cndmask_b32_e64 v131, 0, v131, s[14:15]
	v_add_u32_e32 v145, 30, v138
	v_add_u32_e32 v146, 31, v138
	v_cmp_gt_u32_e32 vcc, s10, v145
	v_cmp_gt_u32_e64 s[14:15], s10, v146
	v_add_u32_e32 v132, 1, v132
	v_add_u32_e32 v133, 1, v133
	v_cndmask_b32_e32 v132, 0, v132, vcc
	v_cndmask_b32_e64 v133, 0, v133, s[14:15]
	v_mov_b32_e32 v141, -1
	v_sub_u32_e32 v142, v141, v102
	v_sub_u32_e32 v145, v141, v103
	v_min_u32_e32 v142, v142, v145
	v_sub_u32_e32 v145, v141, v104
	v_sub_u32_e32 v146, v141, v105
	v_min3_u32 v142, v142, v145, v146
	v_sub_u32_e32 v145, v141, v106
	v_sub_u32_e32 v146, v141, v107
	v_min3_u32 v142, v142, v145, v146
	v_sub_u32_e32 v145, v141, v108
	v_sub_u32_e32 v146, v141, v109
	v_min3_u32 v142, v142, v145, v146
	v_sub_u32_e32 v145, v141, v110
	v_sub_u32_e32 v146, v141, v111
	v_min3_u32 v142, v142, v145, v146
	v_sub_u32_e32 v145, v141, v112
	v_sub_u32_e32 v146, v141, v113
	v_min3_u32 v142, v142, v145, v146
	v_sub_u32_e32 v145, v141, v114
	v_sub_u32_e32 v146, v141, v115
	v_min3_u32 v142, v142, v145, v146
	v_sub_u32_e32 v145, v141, v116
	v_sub_u32_e32 v146, v141, v117
	v_min3_u32 v142, v142, v145, v146
	v_sub_u32_e32 v145, v141, v118
	v_sub_u32_e32 v146, v141, v119
	v_min3_u32 v142, v142, v145, v146
	v_sub_u32_e32 v145, v141, v120
	v_sub_u32_e32 v146, v141, v121
	v_min3_u32 v142, v142, v145, v146
	v_sub_u32_e32 v145, v141, v122
	v_sub_u32_e32 v146, v141, v123
	v_min3_u32 v142, v142, v145, v146
	v_sub_u32_e32 v145, v141, v124
	v_sub_u32_e32 v146, v141, v125
	v_min3_u32 v142, v142, v145, v146
	v_sub_u32_e32 v145, v141, v126
	v_sub_u32_e32 v146, v141, v127
	v_min3_u32 v142, v142, v145, v146
	v_sub_u32_e32 v145, v141, v128
	v_sub_u32_e32 v146, v141, v129
	v_min3_u32 v142, v142, v145, v146
	v_sub_u32_e32 v145, v141, v130
	v_sub_u32_e32 v146, v141, v131
	v_min3_u32 v142, v142, v145, v146
	v_sub_u32_e32 v145, v141, v132
	v_sub_u32_e32 v146, v141, v133
	v_min3_u32 v142, v142, v145, v146
	s_nop 1
	v_min_u32_dpp v142, v142, v142 quad_perm:[1,0,3,2] row_mask:0xf bank_mask:0xf
	s_nop 1
	v_min_u32_dpp v142, v142, v142 quad_perm:[2,3,0,1] row_mask:0xf bank_mask:0xf
	s_nop 1
	v_min_u32_dpp v142, v142, v142 row_half_mirror row_mask:0xf bank_mask:0xf
	v_sub_u32_e32 v143, v141, v142
	v_add_u32_e32 v141, -1, v143
	v_sub_u32_e32 v142, v141, v102
	v_sub_u32_e32 v145, v141, v103
	v_min_u32_e32 v142, v142, v145
	v_sub_u32_e32 v145, v141, v104
	v_sub_u32_e32 v146, v141, v105
	v_min3_u32 v142, v142, v145, v146
	v_sub_u32_e32 v145, v141, v106
	v_sub_u32_e32 v146, v141, v107
	v_min3_u32 v142, v142, v145, v146
	v_sub_u32_e32 v145, v141, v108
	v_sub_u32_e32 v146, v141, v109
	v_min3_u32 v142, v142, v145, v146
	v_sub_u32_e32 v145, v141, v110
	v_sub_u32_e32 v146, v141, v111
	v_min3_u32 v142, v142, v145, v146
	v_sub_u32_e32 v145, v141, v112
	v_sub_u32_e32 v146, v141, v113
	v_min3_u32 v142, v142, v145, v146
	v_sub_u32_e32 v145, v141, v114
	v_sub_u32_e32 v146, v141, v115
	v_min3_u32 v142, v142, v145, v146
	v_sub_u32_e32 v145, v141, v116
	v_sub_u32_e32 v146, v141, v117
	v_min3_u32 v142, v142, v145, v146
	v_sub_u32_e32 v145, v141, v118
	v_sub_u32_e32 v146, v141, v119
	v_min3_u32 v142, v142, v145, v146
	v_sub_u32_e32 v145, v141, v120
	v_sub_u32_e32 v146, v141, v121
	v_min3_u32 v142, v142, v145, v146
	v_sub_u32_e32 v145, v141, v122
	v_sub_u32_e32 v146, v141, v123
	v_min3_u32 v142, v142, v145, v146
	v_sub_u32_e32 v145, v141, v124
	v_sub_u32_e32 v146, v141, v125
	v_min3_u32 v142, v142, v145, v146
	v_sub_u32_e32 v145, v141, v126
	v_sub_u32_e32 v146, v141, v127
	v_min3_u32 v142, v142, v145, v146
	v_sub_u32_e32 v145, v141, v128
	v_sub_u32_e32 v146, v141, v129
	v_min3_u32 v142, v142, v145, v146
	v_sub_u32_e32 v145, v141, v130
	v_sub_u32_e32 v146, v141, v131
	v_min3_u32 v142, v142, v145, v146
	v_sub_u32_e32 v145, v141, v132
	v_sub_u32_e32 v146, v141, v133
	v_min3_u32 v142, v142, v145, v146
	s_nop 1
	v_min_u32_dpp v142, v142, v142 quad_perm:[1,0,3,2] row_mask:0xf bank_mask:0xf
	s_nop 1
	v_min_u32_dpp v142, v142, v142 quad_perm:[2,3,0,1] row_mask:0xf bank_mask:0xf
	s_nop 1
	v_min_u32_dpp v142, v142, v142 row_half_mirror row_mask:0xf bank_mask:0xf
	v_sub_u32_e32 v143, v141, v142
	v_add_u32_e32 v141, -1, v143
	v_sub_u32_e32 v142, v141, v102
	v_sub_u32_e32 v145, v141, v103
	v_min_u32_e32 v142, v142, v145
	v_sub_u32_e32 v145, v141, v104
	v_sub_u32_e32 v146, v141, v105
	v_min3_u32 v142, v142, v145, v146
	v_sub_u32_e32 v145, v141, v106
	v_sub_u32_e32 v146, v141, v107
	v_min3_u32 v142, v142, v145, v146
	v_sub_u32_e32 v145, v141, v108
	v_sub_u32_e32 v146, v141, v109
	v_min3_u32 v142, v142, v145, v146
	v_sub_u32_e32 v145, v141, v110
	v_sub_u32_e32 v146, v141, v111
	v_min3_u32 v142, v142, v145, v146
	v_sub_u32_e32 v145, v141, v112
	v_sub_u32_e32 v146, v141, v113
	v_min3_u32 v142, v142, v145, v146
	v_sub_u32_e32 v145, v141, v114
	v_sub_u32_e32 v146, v141, v115
	v_min3_u32 v142, v142, v145, v146
	v_sub_u32_e32 v145, v141, v116
	v_sub_u32_e32 v146, v141, v117
	v_min3_u32 v142, v142, v145, v146
	v_sub_u32_e32 v145, v141, v118
	v_sub_u32_e32 v146, v141, v119
	v_min3_u32 v142, v142, v145, v146
	v_sub_u32_e32 v145, v141, v120
	v_sub_u32_e32 v146, v141, v121
	v_min3_u32 v142, v142, v145, v146
	v_sub_u32_e32 v145, v141, v122
	v_sub_u32_e32 v146, v141, v123
	v_min3_u32 v142, v142, v145, v146
	v_sub_u32_e32 v145, v141, v124
	v_sub_u32_e32 v146, v141, v125
	v_min3_u32 v142, v142, v145, v146
	v_sub_u32_e32 v145, v141, v126
	v_sub_u32_e32 v146, v141, v127
	v_min3_u32 v142, v142, v145, v146
	v_sub_u32_e32 v145, v141, v128
	v_sub_u32_e32 v146, v141, v129
	v_min3_u32 v142, v142, v145, v146
	v_sub_u32_e32 v145, v141, v130
	v_sub_u32_e32 v146, v141, v131
	v_min3_u32 v142, v142, v145, v146
	v_sub_u32_e32 v145, v141, v132
	v_sub_u32_e32 v146, v141, v133
	v_min3_u32 v142, v142, v145, v146
	s_nop 1
	v_min_u32_dpp v142, v142, v142 quad_perm:[1,0,3,2] row_mask:0xf bank_mask:0xf
	s_nop 1
	v_min_u32_dpp v142, v142, v142 quad_perm:[2,3,0,1] row_mask:0xf bank_mask:0xf
	s_nop 1
	v_min_u32_dpp v142, v142, v142 row_half_mirror row_mask:0xf bank_mask:0xf
	v_sub_u32_e32 v143, v141, v142
	v_add_u32_e32 v141, -1, v143
	v_sub_u32_e32 v142, v141, v102
	v_sub_u32_e32 v145, v141, v103
	v_min_u32_e32 v142, v142, v145
	v_sub_u32_e32 v145, v141, v104
	v_sub_u32_e32 v146, v141, v105
	v_min3_u32 v142, v142, v145, v146
	v_sub_u32_e32 v145, v141, v106
	v_sub_u32_e32 v146, v141, v107
	v_min3_u32 v142, v142, v145, v146
	v_sub_u32_e32 v145, v141, v108
	v_sub_u32_e32 v146, v141, v109
	v_min3_u32 v142, v142, v145, v146
	v_sub_u32_e32 v145, v141, v110
	v_sub_u32_e32 v146, v141, v111
	v_min3_u32 v142, v142, v145, v146
	v_sub_u32_e32 v145, v141, v112
	v_sub_u32_e32 v146, v141, v113
	v_min3_u32 v142, v142, v145, v146
	v_sub_u32_e32 v145, v141, v114
	v_sub_u32_e32 v146, v141, v115
	v_min3_u32 v142, v142, v145, v146
	v_sub_u32_e32 v145, v141, v116
	v_sub_u32_e32 v146, v141, v117
	v_min3_u32 v142, v142, v145, v146
	v_sub_u32_e32 v145, v141, v118
	v_sub_u32_e32 v146, v141, v119
	v_min3_u32 v142, v142, v145, v146
	v_sub_u32_e32 v145, v141, v120
	v_sub_u32_e32 v146, v141, v121
	v_min3_u32 v142, v142, v145, v146
	v_sub_u32_e32 v145, v141, v122
	v_sub_u32_e32 v146, v141, v123
	v_min3_u32 v142, v142, v145, v146
	v_sub_u32_e32 v145, v141, v124
	v_sub_u32_e32 v146, v141, v125
	v_min3_u32 v142, v142, v145, v146
	v_sub_u32_e32 v145, v141, v126
	v_sub_u32_e32 v146, v141, v127
	v_min3_u32 v142, v142, v145, v146
	v_sub_u32_e32 v145, v141, v128
	v_sub_u32_e32 v146, v141, v129
	v_min3_u32 v142, v142, v145, v146
	v_sub_u32_e32 v145, v141, v130
	v_sub_u32_e32 v146, v141, v131
	v_min3_u32 v142, v142, v145, v146
	v_sub_u32_e32 v145, v141, v132
	v_sub_u32_e32 v146, v141, v133
	v_min3_u32 v142, v142, v145, v146
	s_nop 1
	v_min_u32_dpp v142, v142, v142 quad_perm:[1,0,3,2] row_mask:0xf bank_mask:0xf
	s_nop 1
	v_min_u32_dpp v142, v142, v142 quad_perm:[2,3,0,1] row_mask:0xf bank_mask:0xf
	s_nop 1
	v_min_u32_dpp v142, v142, v142 row_half_mirror row_mask:0xf bank_mask:0xf
	v_sub_u32_e32 v143, v141, v142
	v_add_u32_e32 v141, -1, v143
	v_sub_u32_e32 v142, v141, v102
	v_sub_u32_e32 v145, v141, v103
	v_min_u32_e32 v142, v142, v145
	v_sub_u32_e32 v145, v141, v104
	v_sub_u32_e32 v146, v141, v105
	v_min3_u32 v142, v142, v145, v146
	v_sub_u32_e32 v145, v141, v106
	v_sub_u32_e32 v146, v141, v107
	v_min3_u32 v142, v142, v145, v146
	v_sub_u32_e32 v145, v141, v108
	v_sub_u32_e32 v146, v141, v109
	v_min3_u32 v142, v142, v145, v146
	v_sub_u32_e32 v145, v141, v110
	v_sub_u32_e32 v146, v141, v111
	v_min3_u32 v142, v142, v145, v146
	v_sub_u32_e32 v145, v141, v112
	v_sub_u32_e32 v146, v141, v113
	v_min3_u32 v142, v142, v145, v146
	v_sub_u32_e32 v145, v141, v114
	v_sub_u32_e32 v146, v141, v115
	v_min3_u32 v142, v142, v145, v146
	v_sub_u32_e32 v145, v141, v116
	v_sub_u32_e32 v146, v141, v117
	v_min3_u32 v142, v142, v145, v146
	v_sub_u32_e32 v145, v141, v118
	v_sub_u32_e32 v146, v141, v119
	v_min3_u32 v142, v142, v145, v146
	v_sub_u32_e32 v145, v141, v120
	v_sub_u32_e32 v146, v141, v121
	v_min3_u32 v142, v142, v145, v146
	v_sub_u32_e32 v145, v141, v122
	v_sub_u32_e32 v146, v141, v123
	v_min3_u32 v142, v142, v145, v146
	v_sub_u32_e32 v145, v141, v124
	v_sub_u32_e32 v146, v141, v125
	v_min3_u32 v142, v142, v145, v146
	v_sub_u32_e32 v145, v141, v126
	v_sub_u32_e32 v146, v141, v127
	v_min3_u32 v142, v142, v145, v146
	v_sub_u32_e32 v145, v141, v128
	v_sub_u32_e32 v146, v141, v129
	v_min3_u32 v142, v142, v145, v146
	v_sub_u32_e32 v145, v141, v130
	v_sub_u32_e32 v146, v141, v131
	v_min3_u32 v142, v142, v145, v146
	v_sub_u32_e32 v145, v141, v132
	v_sub_u32_e32 v146, v141, v133
	v_min3_u32 v142, v142, v145, v146
	s_nop 1
	v_min_u32_dpp v142, v142, v142 quad_perm:[1,0,3,2] row_mask:0xf bank_mask:0xf
	s_nop 1
	v_min_u32_dpp v142, v142, v142 quad_perm:[2,3,0,1] row_mask:0xf bank_mask:0xf
	s_nop 1
	v_min_u32_dpp v142, v142, v142 row_half_mirror row_mask:0xf bank_mask:0xf
	v_sub_u32_e32 v143, v141, v142
	v_add_u32_e32 v141, -1, v143
	v_sub_u32_e32 v142, v141, v102
	v_sub_u32_e32 v145, v141, v103
	v_min_u32_e32 v142, v142, v145
	v_sub_u32_e32 v145, v141, v104
	v_sub_u32_e32 v146, v141, v105
	v_min3_u32 v142, v142, v145, v146
	v_sub_u32_e32 v145, v141, v106
	v_sub_u32_e32 v146, v141, v107
	v_min3_u32 v142, v142, v145, v146
	v_sub_u32_e32 v145, v141, v108
	v_sub_u32_e32 v146, v141, v109
	v_min3_u32 v142, v142, v145, v146
	v_sub_u32_e32 v145, v141, v110
	v_sub_u32_e32 v146, v141, v111
	v_min3_u32 v142, v142, v145, v146
	v_sub_u32_e32 v145, v141, v112
	v_sub_u32_e32 v146, v141, v113
	v_min3_u32 v142, v142, v145, v146
	v_sub_u32_e32 v145, v141, v114
	v_sub_u32_e32 v146, v141, v115
	v_min3_u32 v142, v142, v145, v146
	v_sub_u32_e32 v145, v141, v116
	v_sub_u32_e32 v146, v141, v117
	v_min3_u32 v142, v142, v145, v146
	v_sub_u32_e32 v145, v141, v118
	v_sub_u32_e32 v146, v141, v119
	v_min3_u32 v142, v142, v145, v146
	v_sub_u32_e32 v145, v141, v120
	v_sub_u32_e32 v146, v141, v121
	v_min3_u32 v142, v142, v145, v146
	v_sub_u32_e32 v145, v141, v122
	v_sub_u32_e32 v146, v141, v123
	v_min3_u32 v142, v142, v145, v146
	v_sub_u32_e32 v145, v141, v124
	v_sub_u32_e32 v146, v141, v125
	v_min3_u32 v142, v142, v145, v146
	v_sub_u32_e32 v145, v141, v126
	v_sub_u32_e32 v146, v141, v127
	v_min3_u32 v142, v142, v145, v146
	v_sub_u32_e32 v145, v141, v128
	v_sub_u32_e32 v146, v141, v129
	v_min3_u32 v142, v142, v145, v146
	v_sub_u32_e32 v145, v141, v130
	v_sub_u32_e32 v146, v141, v131
	v_min3_u32 v142, v142, v145, v146
	v_sub_u32_e32 v145, v141, v132
	v_sub_u32_e32 v146, v141, v133
	v_min3_u32 v142, v142, v145, v146
	s_nop 1
	v_min_u32_dpp v142, v142, v142 quad_perm:[1,0,3,2] row_mask:0xf bank_mask:0xf
	s_nop 1
	v_min_u32_dpp v142, v142, v142 quad_perm:[2,3,0,1] row_mask:0xf bank_mask:0xf
	s_nop 1
	v_min_u32_dpp v142, v142, v142 row_half_mirror row_mask:0xf bank_mask:0xf
	v_sub_u32_e32 v143, v141, v142
	v_add_u32_e32 v141, -1, v143
	v_sub_u32_e32 v142, v141, v102
	v_sub_u32_e32 v145, v141, v103
	v_min_u32_e32 v142, v142, v145
	v_sub_u32_e32 v145, v141, v104
	v_sub_u32_e32 v146, v141, v105
	v_min3_u32 v142, v142, v145, v146
	v_sub_u32_e32 v145, v141, v106
	v_sub_u32_e32 v146, v141, v107
	v_min3_u32 v142, v142, v145, v146
	v_sub_u32_e32 v145, v141, v108
	v_sub_u32_e32 v146, v141, v109
	v_min3_u32 v142, v142, v145, v146
	v_sub_u32_e32 v145, v141, v110
	v_sub_u32_e32 v146, v141, v111
	v_min3_u32 v142, v142, v145, v146
	v_sub_u32_e32 v145, v141, v112
	v_sub_u32_e32 v146, v141, v113
	v_min3_u32 v142, v142, v145, v146
	v_sub_u32_e32 v145, v141, v114
	v_sub_u32_e32 v146, v141, v115
	v_min3_u32 v142, v142, v145, v146
	v_sub_u32_e32 v145, v141, v116
	v_sub_u32_e32 v146, v141, v117
	v_min3_u32 v142, v142, v145, v146
	v_sub_u32_e32 v145, v141, v118
	v_sub_u32_e32 v146, v141, v119
	v_min3_u32 v142, v142, v145, v146
	v_sub_u32_e32 v145, v141, v120
	v_sub_u32_e32 v146, v141, v121
	v_min3_u32 v142, v142, v145, v146
	v_sub_u32_e32 v145, v141, v122
	v_sub_u32_e32 v146, v141, v123
	v_min3_u32 v142, v142, v145, v146
	v_sub_u32_e32 v145, v141, v124
	v_sub_u32_e32 v146, v141, v125
	v_min3_u32 v142, v142, v145, v146
	v_sub_u32_e32 v145, v141, v126
	v_sub_u32_e32 v146, v141, v127
	v_min3_u32 v142, v142, v145, v146
	v_sub_u32_e32 v145, v141, v128
	v_sub_u32_e32 v146, v141, v129
	v_min3_u32 v142, v142, v145, v146
	v_sub_u32_e32 v145, v141, v130
	v_sub_u32_e32 v146, v141, v131
	v_min3_u32 v142, v142, v145, v146
	v_sub_u32_e32 v145, v141, v132
	v_sub_u32_e32 v146, v141, v133
	v_min3_u32 v142, v142, v145, v146
	s_nop 1
	v_min_u32_dpp v142, v142, v142 quad_perm:[1,0,3,2] row_mask:0xf bank_mask:0xf
	s_nop 1
	v_min_u32_dpp v142, v142, v142 quad_perm:[2,3,0,1] row_mask:0xf bank_mask:0xf
	s_nop 1
	v_min_u32_dpp v142, v142, v142 row_half_mirror row_mask:0xf bank_mask:0xf
	v_sub_u32_e32 v143, v141, v142
	v_add_u32_e32 v141, -1, v143
	v_sub_u32_e32 v142, v141, v102
	v_sub_u32_e32 v145, v141, v103
	v_min_u32_e32 v142, v142, v145
	v_sub_u32_e32 v145, v141, v104
	v_sub_u32_e32 v146, v141, v105
	v_min3_u32 v142, v142, v145, v146
	v_sub_u32_e32 v145, v141, v106
	v_sub_u32_e32 v146, v141, v107
	v_min3_u32 v142, v142, v145, v146
	v_sub_u32_e32 v145, v141, v108
	v_sub_u32_e32 v146, v141, v109
	v_min3_u32 v142, v142, v145, v146
	v_sub_u32_e32 v145, v141, v110
	v_sub_u32_e32 v146, v141, v111
	v_min3_u32 v142, v142, v145, v146
	v_sub_u32_e32 v145, v141, v112
	v_sub_u32_e32 v146, v141, v113
	v_min3_u32 v142, v142, v145, v146
	v_sub_u32_e32 v145, v141, v114
	v_sub_u32_e32 v146, v141, v115
	v_min3_u32 v142, v142, v145, v146
	v_sub_u32_e32 v145, v141, v116
	v_sub_u32_e32 v146, v141, v117
	v_min3_u32 v142, v142, v145, v146
	v_sub_u32_e32 v145, v141, v118
	v_sub_u32_e32 v146, v141, v119
	v_min3_u32 v142, v142, v145, v146
	v_sub_u32_e32 v145, v141, v120
	v_sub_u32_e32 v146, v141, v121
	v_min3_u32 v142, v142, v145, v146
	v_sub_u32_e32 v145, v141, v122
	v_sub_u32_e32 v146, v141, v123
	v_min3_u32 v142, v142, v145, v146
	v_sub_u32_e32 v145, v141, v124
	v_sub_u32_e32 v146, v141, v125
	v_min3_u32 v142, v142, v145, v146
	v_sub_u32_e32 v145, v141, v126
	v_sub_u32_e32 v146, v141, v127
	v_min3_u32 v142, v142, v145, v146
	v_sub_u32_e32 v145, v141, v128
	v_sub_u32_e32 v146, v141, v129
	v_min3_u32 v142, v142, v145, v146
	v_sub_u32_e32 v145, v141, v130
	v_sub_u32_e32 v146, v141, v131
	v_min3_u32 v142, v142, v145, v146
	v_sub_u32_e32 v145, v141, v132
	v_sub_u32_e32 v146, v141, v133
	v_min3_u32 v142, v142, v145, v146
	s_nop 1
	v_min_u32_dpp v142, v142, v142 quad_perm:[1,0,3,2] row_mask:0xf bank_mask:0xf
	s_nop 1
	v_min_u32_dpp v142, v142, v142 quad_perm:[2,3,0,1] row_mask:0xf bank_mask:0xf
	s_nop 1
	v_min_u32_dpp v142, v142, v142 row_half_mirror row_mask:0xf bank_mask:0xf
	v_sub_u32_e32 v143, v141, v142
	v_add_u32_e32 v141, -1, v143
	v_sub_u32_e32 v142, v141, v102
	v_sub_u32_e32 v145, v141, v103
	v_min_u32_e32 v142, v142, v145
	v_sub_u32_e32 v145, v141, v104
	v_sub_u32_e32 v146, v141, v105
	v_min3_u32 v142, v142, v145, v146
	v_sub_u32_e32 v145, v141, v106
	v_sub_u32_e32 v146, v141, v107
	v_min3_u32 v142, v142, v145, v146
	v_sub_u32_e32 v145, v141, v108
	v_sub_u32_e32 v146, v141, v109
	v_min3_u32 v142, v142, v145, v146
	v_sub_u32_e32 v145, v141, v110
	v_sub_u32_e32 v146, v141, v111
	v_min3_u32 v142, v142, v145, v146
	v_sub_u32_e32 v145, v141, v112
	v_sub_u32_e32 v146, v141, v113
	v_min3_u32 v142, v142, v145, v146
	v_sub_u32_e32 v145, v141, v114
	v_sub_u32_e32 v146, v141, v115
	v_min3_u32 v142, v142, v145, v146
	v_sub_u32_e32 v145, v141, v116
	v_sub_u32_e32 v146, v141, v117
	v_min3_u32 v142, v142, v145, v146
	v_sub_u32_e32 v145, v141, v118
	v_sub_u32_e32 v146, v141, v119
	v_min3_u32 v142, v142, v145, v146
	v_sub_u32_e32 v145, v141, v120
	v_sub_u32_e32 v146, v141, v121
	v_min3_u32 v142, v142, v145, v146
	v_sub_u32_e32 v145, v141, v122
	v_sub_u32_e32 v146, v141, v123
	v_min3_u32 v142, v142, v145, v146
	v_sub_u32_e32 v145, v141, v124
	v_sub_u32_e32 v146, v141, v125
	v_min3_u32 v142, v142, v145, v146
	v_sub_u32_e32 v145, v141, v126
	v_sub_u32_e32 v146, v141, v127
	v_min3_u32 v142, v142, v145, v146
	v_sub_u32_e32 v145, v141, v128
	v_sub_u32_e32 v146, v141, v129
	v_min3_u32 v142, v142, v145, v146
	v_sub_u32_e32 v145, v141, v130
	v_sub_u32_e32 v146, v141, v131
	v_min3_u32 v142, v142, v145, v146
	v_sub_u32_e32 v145, v141, v132
	v_sub_u32_e32 v146, v141, v133
	v_min3_u32 v142, v142, v145, v146
	s_nop 1
	v_min_u32_dpp v142, v142, v142 quad_perm:[1,0,3,2] row_mask:0xf bank_mask:0xf
	s_nop 1
	v_min_u32_dpp v142, v142, v142 quad_perm:[2,3,0,1] row_mask:0xf bank_mask:0xf
	s_nop 1
	v_min_u32_dpp v142, v142, v142 row_half_mirror row_mask:0xf bank_mask:0xf
	v_sub_u32_e32 v143, v141, v142
	v_add_u32_e32 v141, -1, v143
	v_sub_u32_e32 v142, v141, v102
	v_sub_u32_e32 v145, v141, v103
	v_min_u32_e32 v142, v142, v145
	v_sub_u32_e32 v145, v141, v104
	v_sub_u32_e32 v146, v141, v105
	v_min3_u32 v142, v142, v145, v146
	v_sub_u32_e32 v145, v141, v106
	v_sub_u32_e32 v146, v141, v107
	v_min3_u32 v142, v142, v145, v146
	v_sub_u32_e32 v145, v141, v108
	v_sub_u32_e32 v146, v141, v109
	v_min3_u32 v142, v142, v145, v146
	v_sub_u32_e32 v145, v141, v110
	v_sub_u32_e32 v146, v141, v111
	v_min3_u32 v142, v142, v145, v146
	v_sub_u32_e32 v145, v141, v112
	v_sub_u32_e32 v146, v141, v113
	v_min3_u32 v142, v142, v145, v146
	v_sub_u32_e32 v145, v141, v114
	v_sub_u32_e32 v146, v141, v115
	v_min3_u32 v142, v142, v145, v146
	v_sub_u32_e32 v145, v141, v116
	v_sub_u32_e32 v146, v141, v117
	v_min3_u32 v142, v142, v145, v146
	v_sub_u32_e32 v145, v141, v118
	v_sub_u32_e32 v146, v141, v119
	v_min3_u32 v142, v142, v145, v146
	v_sub_u32_e32 v145, v141, v120
	v_sub_u32_e32 v146, v141, v121
	v_min3_u32 v142, v142, v145, v146
	v_sub_u32_e32 v145, v141, v122
	v_sub_u32_e32 v146, v141, v123
	v_min3_u32 v142, v142, v145, v146
	v_sub_u32_e32 v145, v141, v124
	v_sub_u32_e32 v146, v141, v125
	v_min3_u32 v142, v142, v145, v146
	v_sub_u32_e32 v145, v141, v126
	v_sub_u32_e32 v146, v141, v127
	v_min3_u32 v142, v142, v145, v146
	v_sub_u32_e32 v145, v141, v128
	v_sub_u32_e32 v146, v141, v129
	v_min3_u32 v142, v142, v145, v146
	v_sub_u32_e32 v145, v141, v130
	v_sub_u32_e32 v146, v141, v131
	v_min3_u32 v142, v142, v145, v146
	v_sub_u32_e32 v145, v141, v132
	v_sub_u32_e32 v146, v141, v133
	v_min3_u32 v142, v142, v145, v146
	s_nop 1
	v_min_u32_dpp v142, v142, v142 quad_perm:[1,0,3,2] row_mask:0xf bank_mask:0xf
	s_nop 1
	v_min_u32_dpp v142, v142, v142 quad_perm:[2,3,0,1] row_mask:0xf bank_mask:0xf
	s_nop 1
	v_min_u32_dpp v142, v142, v142 row_half_mirror row_mask:0xf bank_mask:0xf
	v_sub_u32_e32 v143, v141, v142
	v_add_u32_e32 v141, -1, v143
	v_sub_u32_e32 v142, v141, v102
	v_sub_u32_e32 v145, v141, v103
	v_min_u32_e32 v142, v142, v145
	v_sub_u32_e32 v145, v141, v104
	v_sub_u32_e32 v146, v141, v105
	v_min3_u32 v142, v142, v145, v146
	v_sub_u32_e32 v145, v141, v106
	v_sub_u32_e32 v146, v141, v107
	v_min3_u32 v142, v142, v145, v146
	v_sub_u32_e32 v145, v141, v108
	v_sub_u32_e32 v146, v141, v109
	v_min3_u32 v142, v142, v145, v146
	v_sub_u32_e32 v145, v141, v110
	v_sub_u32_e32 v146, v141, v111
	v_min3_u32 v142, v142, v145, v146
	v_sub_u32_e32 v145, v141, v112
	v_sub_u32_e32 v146, v141, v113
	v_min3_u32 v142, v142, v145, v146
	v_sub_u32_e32 v145, v141, v114
	v_sub_u32_e32 v146, v141, v115
	v_min3_u32 v142, v142, v145, v146
	v_sub_u32_e32 v145, v141, v116
	v_sub_u32_e32 v146, v141, v117
	v_min3_u32 v142, v142, v145, v146
	v_sub_u32_e32 v145, v141, v118
	v_sub_u32_e32 v146, v141, v119
	v_min3_u32 v142, v142, v145, v146
	v_sub_u32_e32 v145, v141, v120
	v_sub_u32_e32 v146, v141, v121
	v_min3_u32 v142, v142, v145, v146
	v_sub_u32_e32 v145, v141, v122
	v_sub_u32_e32 v146, v141, v123
	v_min3_u32 v142, v142, v145, v146
	v_sub_u32_e32 v145, v141, v124
	v_sub_u32_e32 v146, v141, v125
	v_min3_u32 v142, v142, v145, v146
	v_sub_u32_e32 v145, v141, v126
	v_sub_u32_e32 v146, v141, v127
	v_min3_u32 v142, v142, v145, v146
	v_sub_u32_e32 v145, v141, v128
	v_sub_u32_e32 v146, v141, v129
	v_min3_u32 v142, v142, v145, v146
	v_sub_u32_e32 v145, v141, v130
	v_sub_u32_e32 v146, v141, v131
	v_min3_u32 v142, v142, v145, v146
	v_sub_u32_e32 v145, v141, v132
	v_sub_u32_e32 v146, v141, v133
	v_min3_u32 v142, v142, v145, v146
	s_nop 1
	v_min_u32_dpp v142, v142, v142 quad_perm:[1,0,3,2] row_mask:0xf bank_mask:0xf
	s_nop 1
	v_min_u32_dpp v142, v142, v142 quad_perm:[2,3,0,1] row_mask:0xf bank_mask:0xf
	s_nop 1
	v_min_u32_dpp v142, v142, v142 row_half_mirror row_mask:0xf bank_mask:0xf
	v_sub_u32_e32 v143, v141, v142
	v_add_u32_e32 v141, -1, v143
	v_sub_u32_e32 v142, v141, v102
	v_sub_u32_e32 v145, v141, v103
	v_min_u32_e32 v142, v142, v145
	v_sub_u32_e32 v145, v141, v104
	v_sub_u32_e32 v146, v141, v105
	v_min3_u32 v142, v142, v145, v146
	v_sub_u32_e32 v145, v141, v106
	v_sub_u32_e32 v146, v141, v107
	v_min3_u32 v142, v142, v145, v146
	v_sub_u32_e32 v145, v141, v108
	v_sub_u32_e32 v146, v141, v109
	v_min3_u32 v142, v142, v145, v146
	v_sub_u32_e32 v145, v141, v110
	v_sub_u32_e32 v146, v141, v111
	v_min3_u32 v142, v142, v145, v146
	v_sub_u32_e32 v145, v141, v112
	v_sub_u32_e32 v146, v141, v113
	v_min3_u32 v142, v142, v145, v146
	v_sub_u32_e32 v145, v141, v114
	v_sub_u32_e32 v146, v141, v115
	v_min3_u32 v142, v142, v145, v146
	v_sub_u32_e32 v145, v141, v116
	v_sub_u32_e32 v146, v141, v117
	v_min3_u32 v142, v142, v145, v146
	v_sub_u32_e32 v145, v141, v118
	v_sub_u32_e32 v146, v141, v119
	v_min3_u32 v142, v142, v145, v146
	v_sub_u32_e32 v145, v141, v120
	v_sub_u32_e32 v146, v141, v121
	v_min3_u32 v142, v142, v145, v146
	v_sub_u32_e32 v145, v141, v122
	v_sub_u32_e32 v146, v141, v123
	v_min3_u32 v142, v142, v145, v146
	v_sub_u32_e32 v145, v141, v124
	v_sub_u32_e32 v146, v141, v125
	v_min3_u32 v142, v142, v145, v146
	v_sub_u32_e32 v145, v141, v126
	v_sub_u32_e32 v146, v141, v127
	v_min3_u32 v142, v142, v145, v146
	v_sub_u32_e32 v145, v141, v128
	v_sub_u32_e32 v146, v141, v129
	v_min3_u32 v142, v142, v145, v146
	v_sub_u32_e32 v145, v141, v130
	v_sub_u32_e32 v146, v141, v131
	v_min3_u32 v142, v142, v145, v146
	v_sub_u32_e32 v145, v141, v132
	v_sub_u32_e32 v146, v141, v133
	v_min3_u32 v142, v142, v145, v146
	s_nop 1
	v_min_u32_dpp v142, v142, v142 quad_perm:[1,0,3,2] row_mask:0xf bank_mask:0xf
	s_nop 1
	v_min_u32_dpp v142, v142, v142 quad_perm:[2,3,0,1] row_mask:0xf bank_mask:0xf
	s_nop 1
	v_min_u32_dpp v142, v142, v142 row_half_mirror row_mask:0xf bank_mask:0xf
	v_sub_u32_e32 v143, v141, v142
	v_add_u32_e32 v141, -1, v143
	v_sub_u32_e32 v142, v141, v102
	v_sub_u32_e32 v145, v141, v103
	v_min_u32_e32 v142, v142, v145
	v_sub_u32_e32 v145, v141, v104
	v_sub_u32_e32 v146, v141, v105
	v_min3_u32 v142, v142, v145, v146
	v_sub_u32_e32 v145, v141, v106
	v_sub_u32_e32 v146, v141, v107
	v_min3_u32 v142, v142, v145, v146
	v_sub_u32_e32 v145, v141, v108
	v_sub_u32_e32 v146, v141, v109
	v_min3_u32 v142, v142, v145, v146
	v_sub_u32_e32 v145, v141, v110
	v_sub_u32_e32 v146, v141, v111
	v_min3_u32 v142, v142, v145, v146
	v_sub_u32_e32 v145, v141, v112
	v_sub_u32_e32 v146, v141, v113
	v_min3_u32 v142, v142, v145, v146
	v_sub_u32_e32 v145, v141, v114
	v_sub_u32_e32 v146, v141, v115
	v_min3_u32 v142, v142, v145, v146
	v_sub_u32_e32 v145, v141, v116
	v_sub_u32_e32 v146, v141, v117
	v_min3_u32 v142, v142, v145, v146
	v_sub_u32_e32 v145, v141, v118
	v_sub_u32_e32 v146, v141, v119
	v_min3_u32 v142, v142, v145, v146
	v_sub_u32_e32 v145, v141, v120
	v_sub_u32_e32 v146, v141, v121
	v_min3_u32 v142, v142, v145, v146
	v_sub_u32_e32 v145, v141, v122
	v_sub_u32_e32 v146, v141, v123
	v_min3_u32 v142, v142, v145, v146
	v_sub_u32_e32 v145, v141, v124
	v_sub_u32_e32 v146, v141, v125
	v_min3_u32 v142, v142, v145, v146
	v_sub_u32_e32 v145, v141, v126
	v_sub_u32_e32 v146, v141, v127
	v_min3_u32 v142, v142, v145, v146
	v_sub_u32_e32 v145, v141, v128
	v_sub_u32_e32 v146, v141, v129
	v_min3_u32 v142, v142, v145, v146
	v_sub_u32_e32 v145, v141, v130
	v_sub_u32_e32 v146, v141, v131
	v_min3_u32 v142, v142, v145, v146
	v_sub_u32_e32 v145, v141, v132
	v_sub_u32_e32 v146, v141, v133
	v_min3_u32 v142, v142, v145, v146
	s_nop 1
	v_min_u32_dpp v142, v142, v142 quad_perm:[1,0,3,2] row_mask:0xf bank_mask:0xf
	s_nop 1
	v_min_u32_dpp v142, v142, v142 quad_perm:[2,3,0,1] row_mask:0xf bank_mask:0xf
	s_nop 1
	v_min_u32_dpp v142, v142, v142 row_half_mirror row_mask:0xf bank_mask:0xf
	v_sub_u32_e32 v143, v141, v142
	v_add_u32_e32 v141, -1, v143
	v_mov_b32_e32 v144, 0
	v_cmp_ge_u32_e64 s[14:15], v102, v143
	v_cmp_ge_u32_e64 s[30:31], v103, v143
	v_cmp_ge_u32_e64 s[56:57], v104, v143
	v_cmp_ge_u32_e64 s[58:59], v105, v143
	v_addc_co_u32_e64 v144, vcc, 0, v144, s[14:15]
	v_addc_co_u32_e64 v144, vcc, 0, v144, s[30:31]
	v_addc_co_u32_e64 v144, vcc, 0, v144, s[56:57]
	v_addc_co_u32_e64 v144, vcc, 0, v144, s[58:59]
	v_cmp_ge_u32_e64 s[14:15], v106, v143
	v_cmp_ge_u32_e64 s[30:31], v107, v143
	v_cmp_ge_u32_e64 s[56:57], v108, v143
	v_cmp_ge_u32_e64 s[58:59], v109, v143
	v_addc_co_u32_e64 v144, vcc, 0, v144, s[14:15]
	v_addc_co_u32_e64 v144, vcc, 0, v144, s[30:31]
	v_addc_co_u32_e64 v144, vcc, 0, v144, s[56:57]
	v_addc_co_u32_e64 v144, vcc, 0, v144, s[58:59]
	v_cmp_ge_u32_e64 s[14:15], v110, v143
	v_cmp_ge_u32_e64 s[30:31], v111, v143
	v_cmp_ge_u32_e64 s[56:57], v112, v143
	v_cmp_ge_u32_e64 s[58:59], v113, v143
	v_addc_co_u32_e64 v144, vcc, 0, v144, s[14:15]
	v_addc_co_u32_e64 v144, vcc, 0, v144, s[30:31]
	v_addc_co_u32_e64 v144, vcc, 0, v144, s[56:57]
	v_addc_co_u32_e64 v144, vcc, 0, v144, s[58:59]
	v_cmp_ge_u32_e64 s[14:15], v114, v143
	v_cmp_ge_u32_e64 s[30:31], v115, v143
	v_cmp_ge_u32_e64 s[56:57], v116, v143
	v_cmp_ge_u32_e64 s[58:59], v117, v143
	v_addc_co_u32_e64 v144, vcc, 0, v144, s[14:15]
	v_addc_co_u32_e64 v144, vcc, 0, v144, s[30:31]
	v_addc_co_u32_e64 v144, vcc, 0, v144, s[56:57]
	v_addc_co_u32_e64 v144, vcc, 0, v144, s[58:59]
	v_cmp_ge_u32_e64 s[14:15], v118, v143
	v_cmp_ge_u32_e64 s[30:31], v119, v143
	v_cmp_ge_u32_e64 s[56:57], v120, v143
	v_cmp_ge_u32_e64 s[58:59], v121, v143
	v_addc_co_u32_e64 v144, vcc, 0, v144, s[14:15]
	v_addc_co_u32_e64 v144, vcc, 0, v144, s[30:31]
	v_addc_co_u32_e64 v144, vcc, 0, v144, s[56:57]
	v_addc_co_u32_e64 v144, vcc, 0, v144, s[58:59]
	v_cmp_ge_u32_e64 s[14:15], v122, v143
	v_cmp_ge_u32_e64 s[30:31], v123, v143
	v_cmp_ge_u32_e64 s[56:57], v124, v143
	v_cmp_ge_u32_e64 s[58:59], v125, v143
	v_addc_co_u32_e64 v144, vcc, 0, v144, s[14:15]
	v_addc_co_u32_e64 v144, vcc, 0, v144, s[30:31]
	v_addc_co_u32_e64 v144, vcc, 0, v144, s[56:57]
	v_addc_co_u32_e64 v144, vcc, 0, v144, s[58:59]
	v_cmp_ge_u32_e64 s[14:15], v126, v143
	v_cmp_ge_u32_e64 s[30:31], v127, v143
	v_cmp_ge_u32_e64 s[56:57], v128, v143
	v_cmp_ge_u32_e64 s[58:59], v129, v143
	v_addc_co_u32_e64 v144, vcc, 0, v144, s[14:15]
	v_addc_co_u32_e64 v144, vcc, 0, v144, s[30:31]
	v_addc_co_u32_e64 v144, vcc, 0, v144, s[56:57]
	v_addc_co_u32_e64 v144, vcc, 0, v144, s[58:59]
	v_cmp_ge_u32_e64 s[14:15], v130, v143
	v_cmp_ge_u32_e64 s[30:31], v131, v143
	v_cmp_ge_u32_e64 s[56:57], v132, v143
	v_cmp_ge_u32_e64 s[58:59], v133, v143
	v_addc_co_u32_e64 v144, vcc, 0, v144, s[14:15]
	v_addc_co_u32_e64 v144, vcc, 0, v144, s[30:31]
	v_addc_co_u32_e64 v144, vcc, 0, v144, s[56:57]
	v_addc_co_u32_e64 v144, vcc, 0, v144, s[58:59]
	s_nop 1
	v_add_u32_dpp v144, v144, v144 quad_perm:[1,0,3,2] row_mask:0xf bank_mask:0xf
	s_nop 1
	v_add_u32_dpp v144, v144, v144 quad_perm:[2,3,0,1] row_mask:0xf bank_mask:0xf
	s_nop 1
	v_add_u32_dpp v144, v144, v144 row_half_mirror row_mask:0xf bank_mask:0xf
	v_cmp_ne_u32_e32 vcc, 13, v144
	s_cmp_lg_u64 vcc, 0
	s_cbranch_scc1 .Ltk8_slow
	v_cmp_ge_u32_e32 vcc, v102, v143
	s_and_saveexec_b64 s[14:15], vcc
	ds_or_b32 v139, v140
	s_mov_b64 exec, s[14:15]
	v_cmp_ge_u32_e32 vcc, v103, v143
	s_and_saveexec_b64 s[14:15], vcc
	ds_or_b32 v139, v140 offset:8
	s_mov_b64 exec, s[14:15]
	v_cmp_ge_u32_e32 vcc, v104, v143
	s_and_saveexec_b64 s[14:15], vcc
	ds_or_b32 v139, v140 offset:16
	s_mov_b64 exec, s[14:15]
	v_cmp_ge_u32_e32 vcc, v105, v143
	s_and_saveexec_b64 s[14:15], vcc
	ds_or_b32 v139, v140 offset:24
	s_mov_b64 exec, s[14:15]
	v_cmp_ge_u32_e32 vcc, v106, v143
	s_and_saveexec_b64 s[14:15], vcc
	ds_or_b32 v139, v140 offset:32
	s_mov_b64 exec, s[14:15]
	v_cmp_ge_u32_e32 vcc, v107, v143
	s_and_saveexec_b64 s[14:15], vcc
	ds_or_b32 v139, v140 offset:40
	s_mov_b64 exec, s[14:15]
	v_cmp_ge_u32_e32 vcc, v108, v143
	s_and_saveexec_b64 s[14:15], vcc
	ds_or_b32 v139, v140 offset:48
	s_mov_b64 exec, s[14:15]
	v_cmp_ge_u32_e32 vcc, v109, v143
	s_and_saveexec_b64 s[14:15], vcc
	ds_or_b32 v139, v140 offset:56
	s_mov_b64 exec, s[14:15]
	v_cmp_ge_u32_e32 vcc, v110, v143
	s_and_saveexec_b64 s[14:15], vcc
	ds_or_b32 v139, v140 offset:64
	s_mov_b64 exec, s[14:15]
	v_cmp_ge_u32_e32 vcc, v111, v143
	s_and_saveexec_b64 s[14:15], vcc
	ds_or_b32 v139, v140 offset:72
	s_mov_b64 exec, s[14:15]
	v_cmp_ge_u32_e32 vcc, v112, v143
	s_and_saveexec_b64 s[14:15], vcc
	ds_or_b32 v139, v140 offset:80
	s_mov_b64 exec, s[14:15]
	v_cmp_ge_u32_e32 vcc, v113, v143
	s_and_saveexec_b64 s[14:15], vcc
	ds_or_b32 v139, v140 offset:88
	s_mov_b64 exec, s[14:15]
	v_cmp_ge_u32_e32 vcc, v114, v143
	s_and_saveexec_b64 s[14:15], vcc
	ds_or_b32 v139, v140 offset:96
	s_mov_b64 exec, s[14:15]
	v_cmp_ge_u32_e32 vcc, v115, v143
	s_and_saveexec_b64 s[14:15], vcc
	ds_or_b32 v139, v140 offset:104
	s_mov_b64 exec, s[14:15]
	v_cmp_ge_u32_e32 vcc, v116, v143
	s_and_saveexec_b64 s[14:15], vcc
	ds_or_b32 v139, v140 offset:112
	s_mov_b64 exec, s[14:15]
	v_cmp_ge_u32_e32 vcc, v117, v143
	s_and_saveexec_b64 s[14:15], vcc
	ds_or_b32 v139, v140 offset:120
	s_mov_b64 exec, s[14:15]
	v_cmp_ge_u32_e32 vcc, v118, v143
	s_and_saveexec_b64 s[14:15], vcc
	ds_or_b32 v139, v140 offset:128
	s_mov_b64 exec, s[14:15]
	v_cmp_ge_u32_e32 vcc, v119, v143
	s_and_saveexec_b64 s[14:15], vcc
	ds_or_b32 v139, v140 offset:136
	s_mov_b64 exec, s[14:15]
	v_cmp_ge_u32_e32 vcc, v120, v143
	s_and_saveexec_b64 s[14:15], vcc
	ds_or_b32 v139, v140 offset:144
	s_mov_b64 exec, s[14:15]
	v_cmp_ge_u32_e32 vcc, v121, v143
	s_and_saveexec_b64 s[14:15], vcc
	ds_or_b32 v139, v140 offset:152
	s_mov_b64 exec, s[14:15]
	v_cmp_ge_u32_e32 vcc, v122, v143
	s_and_saveexec_b64 s[14:15], vcc
	ds_or_b32 v139, v140 offset:160
	s_mov_b64 exec, s[14:15]
	v_cmp_ge_u32_e32 vcc, v123, v143
	s_and_saveexec_b64 s[14:15], vcc
	ds_or_b32 v139, v140 offset:168
	s_mov_b64 exec, s[14:15]
	v_cmp_ge_u32_e32 vcc, v124, v143
	s_and_saveexec_b64 s[14:15], vcc
	ds_or_b32 v139, v140 offset:176
	s_mov_b64 exec, s[14:15]
	v_cmp_ge_u32_e32 vcc, v125, v143
	s_and_saveexec_b64 s[14:15], vcc
	ds_or_b32 v139, v140 offset:184
	s_mov_b64 exec, s[14:15]
	v_cmp_ge_u32_e32 vcc, v126, v143
	s_and_saveexec_b64 s[14:15], vcc
	ds_or_b32 v139, v140 offset:192
	s_mov_b64 exec, s[14:15]
	v_cmp_ge_u32_e32 vcc, v127, v143
	s_and_saveexec_b64 s[14:15], vcc
	ds_or_b32 v139, v140 offset:200
	s_mov_b64 exec, s[14:15]
	v_cmp_ge_u32_e32 vcc, v128, v143
	s_and_saveexec_b64 s[14:15], vcc
	ds_or_b32 v139, v140 offset:208
	s_mov_b64 exec, s[14:15]
	v_cmp_ge_u32_e32 vcc, v129, v143
	s_and_saveexec_b64 s[14:15], vcc
	ds_or_b32 v139, v140 offset:216
	s_mov_b64 exec, s[14:15]
	v_cmp_ge_u32_e32 vcc, v130, v143
	s_and_saveexec_b64 s[14:15], vcc
	ds_or_b32 v139, v140 offset:224
	s_mov_b64 exec, s[14:15]
	v_cmp_ge_u32_e32 vcc, v131, v143
	s_and_saveexec_b64 s[14:15], vcc
	ds_or_b32 v139, v140 offset:232
	s_mov_b64 exec, s[14:15]
	v_cmp_ge_u32_e32 vcc, v132, v143
	s_and_saveexec_b64 s[14:15], vcc
	ds_or_b32 v139, v140 offset:240
	s_mov_b64 exec, s[14:15]
	v_cmp_ge_u32_e32 vcc, v133, v143
	s_and_saveexec_b64 s[14:15], vcc
	ds_or_b32 v139, v140 offset:248
	s_mov_b64 exec, s[14:15]
	s_branch .LBB0_1296

.LBB0_1317:
	v_ashrrev_i32_e32 v219, 31, v218
	v_ashrrev_i32_e32 v215, 31, v214
	s_lshl_b32 s1, s10, 21
	s_add_u32 s8, s36, s1
	s_addc_u32 s9, s37, 0
	s_add_u32 s11, s40, s1
	s_addc_u32 s12, s41, 0
	s_movk_i32 s82, 0x660
	s_waitcnt vmcnt(0)
	v_lshlrev_b32_e32 v2, 4, v199
	v_mov_b32_e32 v22, v218
	v_and_b32_e32 v24, 31, v199
	v_mul_u32_u24_e32 v25, 43, v24
	v_lshrrev_b32_e32 v25, 8, v25
	v_mad_i32_i24 v24, v25, -6, v24
	v_and_b32_e32 v28, 31, v199
	v_cmp_gt_u32_e64 s[94:95], 30, v28
	v_lshlrev_b32_e64 v23, v25, 1
	v_mov_b32_e32 v19, 0x110
	v_cndmask_b32_e64 v25, 0, v25, s[94:95]
	v_mul_u32_u24_e32 v18, 6, v25
	v_mul_u32_u24_e32 v19, v19, v24
	v_lshl_add_u32 v19, v206, 2, v19
	v_add_u32_e32 v19, 0x4000, v19
	s_mul_i32 s0, s10, 6
	v_add_u32_e32 v20, s0, v24
	v_lshl_add_u32 v20, v20, 7, v210
	v_mov_b32_e32 v31, 0x110
	v_mul_u32_u24_e32 v31, v31, v24
	v_add_u32_e32 v31, 0x4100, v31
	v_add_u32_e32 v31, v31, v206
	s_lshl_b32 s90, s77, 8
	s_add_i32 s90, s90, 0x1e000
	s_cmp_eq_u32 s96, 1
	s_cbranch_scc0 .Lq_nozero
	v_mov_b32_e32 v82, 0
	v_mov_b32_e32 v83, 0
	v_mov_b32_e32 v84, 0
	v_mov_b32_e32 v85, 0
	s_lshl_b32 s0, s77, 10
	s_add_i32 s0, s0, 0x4000
	v_add_u32_e32 v28, s0, v2
	v_add_u32_e32 v29, 0x10000, v28
	ds_write_b128 v28, v[82:85]
	ds_write_b128 v28, v[82:85] offset:8192
	ds_write_b128 v28, v[82:85] offset:16384
	ds_write_b128 v28, v[82:85] offset:24576
	ds_write_b128 v28, v[82:85] offset:32768
	ds_write_b128 v28, v[82:85] offset:40960
	ds_write_b128 v28, v[82:85] offset:49152
	ds_write_b128 v28, v[82:85] offset:57344
	ds_write_b128 v29, v[82:85]
	ds_write_b128 v29, v[82:85] offset:8192
	ds_write_b128 v29, v[82:85] offset:16384
	ds_write_b128 v29, v[82:85] offset:24576
	ds_write_b128 v29, v[82:85] offset:32768
	v_mov_b32_e32 v86, 0x1800
	ds_write_b32 v86, v82
	ds_write_b64 v86, v[82:83] offset:8
	v_lshl_add_u32 v122, v199, 2, s90
	ds_write_b32 v122, v82
	s_waitcnt lgkmcnt(0)
	s_barrier
.Lq_nozero:
	v_and_b32_e32 v102, 31, v199
	s_lshl_b32 s0, s77, 5
	v_add_u32_e32 v103, s0, v102
	s_mov_b64 s[58:59], exec
	v_cmp_gt_u32_e32 vcc, 32, v199
	s_and_b64 exec, exec, vcc
	v_lshlrev_b32_e32 v106, 3, v103
	ds_read_b64 v[104:105], v106
	s_waitcnt lgkmcnt(0)
	v_bcnt_u32_b32 v107, v104, 0
	v_bcnt_u32_b32 v107, v105, v107
	v_add_u32_e32 v108, 4, v107
	v_mul_u32_u24_e32 v108, 0xcd, v108
	v_lshrrev_b32_e32 v108, 10, v108
	v_cmp_eq_u32_e64 s[92:93], 64, v107
	v_mov_b32_e32 v110, 0x1800
	ds_add_rtn_u32 v109, v110, v108
	v_cndmask_b32_e64 v107, v107, 0, s[92:93]
	s_waitcnt lgkmcnt(0)
.Lq_build:
	v_cmp_ne_u32_e32 vcc, 0, v107
	s_and_b64 exec, exec, vcc
	s_cbranch_execz .Lq_build_done
	v_mov_b32_e32 v118, 0
	v_mov_b32_e32 v119, 0
	v_cmp_ne_u32_e32 vcc, 0, v104
	v_cmp_ne_u32_e64 s[14:15], 0, v107
	v_ffbl_b32_e32 v111, v104
	v_ffbl_b32_e32 v112, v105
	v_add_u32_e32 v112, 32, v112
	v_cndmask_b32_e32 v111, v112, v111, vcc
	v_lshlrev_b32_e64 v113, v111, 1
	v_not_b32_e32 v113, v113
	v_cndmask_b32_e32 v114, -1, v113, vcc
	v_cndmask_b32_e64 v115, v113, -1, vcc
	v_and_b32_e32 v104, v104, v114
	v_and_b32_e32 v105, v105, v115
	v_lshlrev_b32_e32 v116, 0, v111
	v_cndmask_b32_e64 v116, 0, v116, s[14:15]
	v_or_b32_e32 v118, v118, v116
	v_cndmask_b32_e64 v117, 0, 1, s[14:15]
	v_add_u32_e32 v119, v119, v117
	v_sub_u32_e32 v107, v107, v117
	v_cmp_ne_u32_e32 vcc, 0, v104
	v_cmp_ne_u32_e64 s[14:15], 0, v107
	v_ffbl_b32_e32 v111, v104
	v_ffbl_b32_e32 v112, v105
	v_add_u32_e32 v112, 32, v112
	v_cndmask_b32_e32 v111, v112, v111, vcc
	v_lshlrev_b32_e64 v113, v111, 1
	v_not_b32_e32 v113, v113
	v_cndmask_b32_e32 v114, -1, v113, vcc
	v_cndmask_b32_e64 v115, v113, -1, vcc
	v_and_b32_e32 v104, v104, v114
	v_and_b32_e32 v105, v105, v115
	v_lshlrev_b32_e32 v116, 6, v111
	v_cndmask_b32_e64 v116, 0, v116, s[14:15]
	v_or_b32_e32 v118, v118, v116
	v_cndmask_b32_e64 v117, 0, 1, s[14:15]
	v_add_u32_e32 v119, v119, v117
	v_sub_u32_e32 v107, v107, v117
	v_cmp_ne_u32_e32 vcc, 0, v104
	v_cmp_ne_u32_e64 s[14:15], 0, v107
	v_ffbl_b32_e32 v111, v104
	v_ffbl_b32_e32 v112, v105
	v_add_u32_e32 v112, 32, v112
	v_cndmask_b32_e32 v111, v112, v111, vcc
	v_lshlrev_b32_e64 v113, v111, 1
	v_not_b32_e32 v113, v113
	v_cndmask_b32_e32 v114, -1, v113, vcc
	v_cndmask_b32_e64 v115, v113, -1, vcc
	v_and_b32_e32 v104, v104, v114
	v_and_b32_e32 v105, v105, v115
	v_lshlrev_b32_e32 v116, 12, v111
	v_cndmask_b32_e64 v116, 0, v116, s[14:15]
	v_or_b32_e32 v118, v118, v116
	v_cndmask_b32_e64 v117, 0, 1, s[14:15]
	v_add_u32_e32 v119, v119, v117
	v_sub_u32_e32 v107, v107, v117
	v_cmp_ne_u32_e32 vcc, 0, v104
	v_cmp_ne_u32_e64 s[14:15], 0, v107
	v_ffbl_b32_e32 v111, v104
	v_ffbl_b32_e32 v112, v105
	v_add_u32_e32 v112, 32, v112
	v_cndmask_b32_e32 v111, v112, v111, vcc
	v_lshlrev_b32_e64 v113, v111, 1
	v_not_b32_e32 v113, v113
	v_cndmask_b32_e32 v114, -1, v113, vcc
	v_cndmask_b32_e64 v115, v113, -1, vcc
	v_and_b32_e32 v104, v104, v114
	v_and_b32_e32 v105, v105, v115
	v_lshlrev_b32_e32 v116, 18, v111
	v_cndmask_b32_e64 v116, 0, v116, s[14:15]
	v_or_b32_e32 v118, v118, v116
	v_cndmask_b32_e64 v117, 0, 1, s[14:15]
	v_add_u32_e32 v119, v119, v117
	v_sub_u32_e32 v107, v107, v117
	v_cmp_ne_u32_e32 vcc, 0, v104
	v_cmp_ne_u32_e64 s[14:15], 0, v107
	v_ffbl_b32_e32 v111, v104
	v_ffbl_b32_e32 v112, v105
	v_add_u32_e32 v112, 32, v112
	v_cndmask_b32_e32 v111, v112, v111, vcc
	v_lshlrev_b32_e64 v113, v111, 1
	v_not_b32_e32 v113, v113
	v_cndmask_b32_e32 v114, -1, v113, vcc
	v_cndmask_b32_e64 v115, v113, -1, vcc
	v_and_b32_e32 v104, v104, v114
	v_and_b32_e32 v105, v105, v115
	v_lshlrev_b32_e32 v116, 24, v111
	v_cndmask_b32_e64 v116, 0, v116, s[14:15]
	v_or_b32_e32 v118, v118, v116
	v_cndmask_b32_e64 v117, 0, 1, s[14:15]
	v_add_u32_e32 v119, v119, v117
	v_sub_u32_e32 v107, v107, v117
	v_lshl_or_b32 v120, v119, 8, v103
	v_mov_b32_e32 v121, v118
	v_lshlrev_b32_e32 v122, 3, v109
	ds_write_b64 v122, v[120:121] offset:2048
	v_add_u32_e32 v109, 1, v109
	s_branch .Lq_build

.Lq_full:
	s_cmp_eq_u64 s[92:93], 0
	s_cbranch_scc1 .Lq_full_done
	s_ff1_i32_b64 s0, s[92:93]
	s_bitset0_b64 s[92:93], s0
	s_nop 3
	v_readlane_b32 s1, v103, s0
	v_readlane_b32 s14, v109, s0
	v_cmp_eq_u32_e32 vcc, 12, v199
	v_mul_u32_u24_e32 v121, 5, v199
	v_mov_b32_e32 v123, 0x1041041
	v_mul_lo_u32 v121, v121, v123
	v_add_u32_e32 v121, 0x40c2040, v121
	v_cndmask_b32_e64 v120, 5, 4, vcc
	s_nop 1
	v_lshl_or_b32 v120, v120, 8, s1
	v_add_lshl_u32 v122, v199, s14, 3
	v_cmp_gt_u32_e32 vcc, 13, v199
	s_and_b64 exec, exec, vcc
	ds_write_b64 v122, v[120:121] offset:2048
	s_mov_b64 exec, s[58:59]
	s_branch .Lq_full

.Lq_again:
	s_mov_b32 s52, 0
	s_mov_b32 s69, 0
	s_min_u32 s14, s69, 63
	s_nop 3
	v_readlane_b32 s30, v33, s14
	s_and_b32 s30, s30, 0xff
	s_lshl_b32 s30, s30, 13
	s_add_u32 s64, s11, s30
	s_addc_u32 s65, s12, 0
	s_add_u32 s66, s8, s30
	s_addc_u32 s67, s9, 0
	global_load_dwordx4 v[178:181], v2, s[64:65]
	global_load_dwordx4 v[174:177], v2, s[64:65] offset:1024
	global_load_dwordx4 v[170:173], v2, s[64:65] offset:2048
	global_load_dwordx4 v[166:169], v2, s[64:65] offset:3072
	global_load_dwordx4 v[146:149], v2, s[66:67]
	global_load_dwordx4 v[142:145], v2, s[66:67] offset:1024
	global_load_dwordx4 v[126:129], v2, s[66:67] offset:2048
	global_load_dwordx4 v[114:117], v2, s[66:67] offset:3072
	s_mov_b32 s69, 0
	s_mov_b32 s93, 0
	s_min_u32 s14, s69, 63
	s_nop 3
	v_readlane_b32 s30, v26, s14
	v_readlane_b32 s31, v27, s14
	s_nop 1
	v_bfe_u32 v28, s31, v18, 6
	v_lshl_add_u32 v29, s99, 6, v28
	v_mad_u32_u24 v29, v29, s47, v20
	global_load_dwordx4 v[4:7], v29, s[20:21]
	global_load_dwordx4 v[8:11], v29, s[20:21] offset:32
	global_load_dwordx4 v[12:15], v29, s[20:21] offset:64
	global_load_dwordx4 v[98:101], v29, s[20:21] offset:96
	s_mov_b32 s69, 0
	s_min_u32 s14, s69, 63
	s_nop 3
	v_readlane_b32 s30, v33, s14
	s_and_b32 s30, s30, 0xff
	s_lshl_b32 s30, s30, 13
	s_or_b32 s30, s30, 0x1000
	s_add_u32 s64, s11, s30
	s_addc_u32 s65, s12, 0
	s_add_u32 s66, s8, s30
	s_addc_u32 s67, s9, 0
	global_load_dwordx4 v[162:165], v2, s[64:65]
	global_load_dwordx4 v[154:157], v2, s[64:65] offset:1024
	global_load_dwordx4 v[150:153], v2, s[64:65] offset:2048
	global_load_dwordx4 v[158:161], v2, s[64:65] offset:3072
	global_load_dwordx4 v[138:141], v2, s[66:67]
	global_load_dwordx4 v[122:125], v2, s[66:67] offset:1024
	global_load_dwordx4 v[110:113], v2, s[66:67] offset:2048
	global_load_dwordx4 v[106:109], v2, s[66:67] offset:3072
	s_mov_b32 s69, 1
	s_min_u32 s14, s69, 63
	s_nop 3
	v_readlane_b32 s30, v33, s14
	s_and_b32 s30, s30, 0xff
	s_lshl_b32 s30, s30, 13
	s_add_u32 s64, s11, s30
	s_addc_u32 s65, s12, 0
	s_add_u32 s66, s8, s30
	s_addc_u32 s67, s9, 0
	global_load_dwordx4 v[194:197], v2, s[64:65]
	global_load_dwordx4 v[190:193], v2, s[64:65] offset:1024
	global_load_dwordx4 v[186:189], v2, s[64:65] offset:2048
	global_load_dwordx4 v[182:185], v2, s[64:65] offset:3072
	global_load_dwordx4 v[134:137], v2, s[66:67]
	global_load_dwordx4 v[130:133], v2, s[66:67] offset:1024
	global_load_dwordx4 v[118:121], v2, s[66:67] offset:2048
	global_load_dwordx4 v[102:105], v2, s[66:67] offset:3072

.Lq_wd_k0p0:
	v_bfe_u32 v28, s57, v18, 6
	v_lshl_add_u32 v218, s99, 6, v28
	v_mad_u32_u24 v21, v28, s82, v19
	v_mad_u32_u24 v32, v28, s82, v31
	v_and_b32_e32 v29, s18, v23
	v_cmp_ne_u32_e64 s[54:55], 0, v29
	s_and_b64 s[54:55], s[54:55], s[94:95]
	s_min_u32 s14, s85, 63
	s_nop 3
	v_readlane_b32 s30, v26, s14
	v_readlane_b32 s31, v27, s14
	s_nop 1
	v_bfe_u32 v28, s31, v18, 6
	v_lshl_add_u32 v29, s99, 6, v28
	v_mad_u32_u24 v29, v29, s47, v20
	global_load_dwordx4 v[238:241], v29, s[20:21]
	global_load_dwordx4 v[242:245], v29, s[20:21] offset:32
	global_load_dwordx4 v[246:249], v29, s[20:21] offset:64
	global_load_dwordx4 v[250:253], v29, s[20:21] offset:96
	s_lshl_b32 s0, s100, 6
	v_or_b32_e32 v237, s0, v206
	v_mov_b32_e32 v221, 0
	s_cmp_lg_u32 s100, s99
	s_cbranch_scc1 .Lq_s0n_k0p0
	v_and_b32_e32 v82, s18, v23
	v_cmp_ne_u32_e32 vcc, 0, v82
	s_and_b64 vcc, s[94:95], vcc
	v_mov_b32 v83, 0
	v_or_b32_e32 v16, 2, v237
	v_cndmask_b32_e32 v82, v236, v222, vcc
	v_sub_f32_e32 v82, v83, v82
	v_mov_b32_e32 v83, v82
	v_mov_b32_e32 v84, v82
	v_mov_b32_e32 v85, v82
	v_mov_b32_e32 v86, v82
	v_mov_b32_e32 v87, v82
	v_mov_b32_e32 v88, v82
	v_mov_b32_e32 v89, v82
	v_mov_b32_e32 v90, v82
	v_mov_b32_e32 v91, v82
	v_mov_b32_e32 v92, v82
	v_mov_b32_e32 v93, v82
	v_mov_b32_e32 v94, v82
	v_mov_b32_e32 v95, v82
	v_mov_b32_e32 v96, v82
	v_mov_b32_e32 v97, v82
	v_cmp_le_i32_e32 vcc, v237, v218
	v_or_b32_e32 v17, 3, v237
	v_mfma_f32_32x32x16_bf16 v[82:97], v[178:181], v[4:7], v[82:97]
	v_or_b32_e32 v30, 8, v237
	v_mfma_f32_32x32x16_bf16 v[82:97], v[174:177], v[8:11], v[82:97]
	v_mfma_f32_32x32x16_bf16 v[82:97], v[170:173], v[12:15], v[82:97]
	v_mfma_f32_32x32x16_bf16 v[82:97], v[166:169], v[98:101], v[82:97]
	s_nop 11
	v_exp_f32_e32 v82, v82
	v_exp_f32_e32 v83, v83
	v_exp_f32_e32 v84, v84
	v_exp_f32_e32 v85, v85
	v_exp_f32_e32 v86, v86
	v_cndmask_b32_e32 v82, 0, v82, vcc
	v_cmp_lt_i32_e32 vcc, v237, v218
	v_exp_f32_e32 v87, v87
	v_exp_f32_e32 v88, v88
	v_cndmask_b32_e32 v83, 0, v83, vcc
	v_cmp_le_i32_e32 vcc, v16, v218
	v_or_b32_e32 v16, 9, v237
	v_exp_f32_e32 v89, v89
	v_cndmask_b32_e32 v84, 0, v84, vcc
	v_cmp_le_i32_e32 vcc, v17, v218
	v_exp_f32_e32 v90, v90
	v_exp_f32_e32 v91, v91
	v_cndmask_b32_e32 v85, 0, v85, vcc
	v_cmp_le_i32_e32 vcc, v30, v218
	v_add_f32_e32 v221, v221, v82
	v_exp_f32_e32 v92, v92
	v_cndmask_b32_e32 v86, 0, v86, vcc
	v_cmp_le_i32_e32 vcc, v16, v218
	v_or_b32_e32 v16, 10, v237
	v_add_f32_e32 v221, v83, v221
	v_cndmask_b32_e32 v87, 0, v87, vcc
	v_cmp_le_i32_e32 vcc, v16, v218
	v_or_b32_e32 v16, 11, v237
	v_exp_f32_e32 v93, v93
	v_cndmask_b32_e32 v88, 0, v88, vcc
	v_cmp_le_i32_e32 vcc, v16, v218
	v_or_b32_e32 v16, 16, v237
	v_add_f32_e32 v221, v84, v221
	v_cndmask_b32_e32 v89, 0, v89, vcc
	v_cmp_le_i32_e32 vcc, v16, v218
	v_or_b32_e32 v16, 17, v237
	v_exp_f32_e32 v94, v94
	v_cndmask_b32_e32 v90, 0, v90, vcc
	v_cmp_le_i32_e32 vcc, v16, v218
	v_or_b32_e32 v16, 18, v237
	v_add_f32_e32 v221, v85, v221
	v_cndmask_b32_e32 v91, 0, v91, vcc
	v_cmp_le_i32_e32 vcc, v16, v218
	v_or_b32_e32 v16, 19, v237
	v_exp_f32_e32 v95, v95
	v_add_f32_e32 v221, v86, v221
	v_cndmask_b32_e32 v92, 0, v92, vcc
	v_cmp_le_i32_e32 vcc, v16, v218
	v_or_b32_e32 v16, 24, v237
	v_cvt_pk_bf16_f32 v82, v82, v83
	v_cvt_pk_bf16_f32 v83, v84, v85
	v_cvt_pk_bf16_f32 v84, v86, v87
	v_cvt_pk_bf16_f32 v85, v88, v89
	v_add_f32_e32 v221, v87, v221
	v_cndmask_b32_e32 v93, 0, v93, vcc
	v_cmp_le_i32_e32 vcc, v16, v218
	v_or_b32_e32 v16, 25, v237
	v_mfma_f32_32x32x16_bf16 v[66:81], v[146:149], v[82:85], 0
	v_add_f32_e32 v221, v88, v221
	v_cndmask_b32_e32 v94, 0, v94, vcc
	v_exp_f32_e32 v86, v96
	v_cmp_le_i32_e32 vcc, v16, v218
	v_or_b32_e32 v88, 26, v237
	v_add_f32_e32 v221, v89, v221
	v_cndmask_b32_e32 v87, 0, v95, vcc
	v_mfma_f32_32x32x16_bf16 v[50:65], v[142:145], v[82:85], 0
	v_cmp_le_i32_e32 vcc, v88, v218
	v_exp_f32_e32 v88, v97
	v_or_b32_e32 v82, 27, v237
	v_cndmask_b32_e32 v86, 0, v86, vcc
	v_cmp_le_i32_e32 vcc, v82, v218
	v_cvt_pk_bf16_f32 v82, v90, v91
	v_cvt_pk_bf16_f32 v83, v92, v93
	v_cndmask_b32_e32 v88, 0, v88, vcc
	v_cvt_pk_bf16_f32 v84, v94, v87
	v_cvt_pk_bf16_f32 v85, v86, v88
	v_add_f32_e32 v221, v90, v221
	v_add_f32_e32 v89, v91, v221
	v_mfma_f32_32x32x16_bf16 v[66:81], v[126:129], v[82:85], v[66:81]
	v_add_f32_e32 v89, v92, v89
	v_add_f32_e32 v89, v93, v89
	v_add_f32_e32 v89, v94, v89
	v_add_f32_e32 v87, v87, v89
	v_add_f32_e32 v86, v86, v87
	v_add_f32_e32 v221, v88, v86
	v_mfma_f32_32x32x16_bf16 v[50:65], v[114:117], v[82:85], v[50:65]
	s_cmp_lg_u32 s85, s86
	s_cbranch_scc1 .Lq_nl0_k0p0
	s_min_u32 s14, s87, 63
	s_nop 3
	v_readlane_b32 s30, v33, s14
	s_and_b32 s30, s30, 0xff
	s_lshl_b32 s30, s30, 13
	s_or_b32 s30, s30, 0x1000
	s_add_u32 s64, s11, s30
	s_addc_u32 s65, s12, 0
	s_add_u32 s66, s8, s30
	s_addc_u32 s67, s9, 0
	global_load_dwordx4 v[178:181], v2, s[64:65]
	global_load_dwordx4 v[174:177], v2, s[64:65] offset:1024
	global_load_dwordx4 v[170:173], v2, s[64:65] offset:2048
	global_load_dwordx4 v[166:169], v2, s[64:65] offset:3072
	global_load_dwordx4 v[146:149], v2, s[66:67]
	global_load_dwordx4 v[142:145], v2, s[66:67] offset:1024
	global_load_dwordx4 v[126:129], v2, s[66:67] offset:2048
	global_load_dwordx4 v[114:117], v2, s[66:67] offset:3072
	s_waitcnt vmcnt(20)
	s_branch .Lq_nl0d_k0p0

.Lq_wd_k0p1:
	v_bfe_u32 v28, s57, v18, 6
	v_lshl_add_u32 v218, s99, 6, v28
	v_mad_u32_u24 v21, v28, s82, v19
	v_mad_u32_u24 v32, v28, s82, v31
	v_and_b32_e32 v29, s18, v23
	v_cmp_ne_u32_e64 s[54:55], 0, v29
	s_and_b64 s[54:55], s[54:55], s[94:95]
	s_min_u32 s14, s85, 63
	s_nop 3
	v_readlane_b32 s30, v26, s14
	v_readlane_b32 s31, v27, s14
	s_nop 1
	v_bfe_u32 v28, s31, v18, 6
	v_lshl_add_u32 v29, s99, 6, v28
	v_mad_u32_u24 v29, v29, s47, v20
	global_load_dwordx4 v[4:7], v29, s[20:21]
	global_load_dwordx4 v[8:11], v29, s[20:21] offset:32
	global_load_dwordx4 v[12:15], v29, s[20:21] offset:64
	global_load_dwordx4 v[98:101], v29, s[20:21] offset:96
	s_lshl_b32 s0, s100, 6
	v_or_b32_e32 v237, s0, v206
	v_mov_b32_e32 v221, 0
	s_cmp_lg_u32 s100, s99
	s_cbranch_scc1 .Lq_s0n_k0p1
	v_and_b32_e32 v82, s18, v23
	v_cmp_ne_u32_e32 vcc, 0, v82
	s_and_b64 vcc, s[94:95], vcc
	v_mov_b32 v83, 0
	v_or_b32_e32 v16, 2, v237
	v_cndmask_b32_e32 v82, v236, v222, vcc
	v_sub_f32_e32 v82, v83, v82
	v_mov_b32_e32 v83, v82
	v_mov_b32_e32 v84, v82
	v_mov_b32_e32 v85, v82
	v_mov_b32_e32 v86, v82
	v_mov_b32_e32 v87, v82
	v_mov_b32_e32 v88, v82
	v_mov_b32_e32 v89, v82
	v_mov_b32_e32 v90, v82
	v_mov_b32_e32 v91, v82
	v_mov_b32_e32 v92, v82
	v_mov_b32_e32 v93, v82
	v_mov_b32_e32 v94, v82
	v_mov_b32_e32 v95, v82
	v_mov_b32_e32 v96, v82
	v_mov_b32_e32 v97, v82
	v_cmp_le_i32_e32 vcc, v237, v218
	v_or_b32_e32 v17, 3, v237
	v_mfma_f32_32x32x16_bf16 v[82:97], v[178:181], v[238:241], v[82:97]
	v_or_b32_e32 v30, 8, v237
	v_mfma_f32_32x32x16_bf16 v[82:97], v[174:177], v[242:245], v[82:97]
	v_mfma_f32_32x32x16_bf16 v[82:97], v[170:173], v[246:249], v[82:97]
	v_mfma_f32_32x32x16_bf16 v[82:97], v[166:169], v[250:253], v[82:97]
	s_nop 11
	v_exp_f32_e32 v82, v82
	v_exp_f32_e32 v83, v83
	v_exp_f32_e32 v84, v84
	v_exp_f32_e32 v85, v85
	v_exp_f32_e32 v86, v86
	v_cndmask_b32_e32 v82, 0, v82, vcc
	v_cmp_lt_i32_e32 vcc, v237, v218
	v_exp_f32_e32 v87, v87
	v_exp_f32_e32 v88, v88
	v_cndmask_b32_e32 v83, 0, v83, vcc
	v_cmp_le_i32_e32 vcc, v16, v218
	v_or_b32_e32 v16, 9, v237
	v_exp_f32_e32 v89, v89
	v_cndmask_b32_e32 v84, 0, v84, vcc
	v_cmp_le_i32_e32 vcc, v17, v218
	v_exp_f32_e32 v90, v90
	v_exp_f32_e32 v91, v91
	v_cndmask_b32_e32 v85, 0, v85, vcc
	v_cmp_le_i32_e32 vcc, v30, v218
	v_add_f32_e32 v221, v221, v82
	v_exp_f32_e32 v92, v92
	v_cndmask_b32_e32 v86, 0, v86, vcc
	v_cmp_le_i32_e32 vcc, v16, v218
	v_or_b32_e32 v16, 10, v237
	v_add_f32_e32 v221, v83, v221
	v_cndmask_b32_e32 v87, 0, v87, vcc
	v_cmp_le_i32_e32 vcc, v16, v218
	v_or_b32_e32 v16, 11, v237
	v_exp_f32_e32 v93, v93
	v_cndmask_b32_e32 v88, 0, v88, vcc
	v_cmp_le_i32_e32 vcc, v16, v218
	v_or_b32_e32 v16, 16, v237
	v_add_f32_e32 v221, v84, v221
	v_cndmask_b32_e32 v89, 0, v89, vcc
	v_cmp_le_i32_e32 vcc, v16, v218
	v_or_b32_e32 v16, 17, v237
	v_exp_f32_e32 v94, v94
	v_cndmask_b32_e32 v90, 0, v90, vcc
	v_cmp_le_i32_e32 vcc, v16, v218
	v_or_b32_e32 v16, 18, v237
	v_add_f32_e32 v221, v85, v221
	v_cndmask_b32_e32 v91, 0, v91, vcc
	v_cmp_le_i32_e32 vcc, v16, v218
	v_or_b32_e32 v16, 19, v237
	v_exp_f32_e32 v95, v95
	v_add_f32_e32 v221, v86, v221
	v_cndmask_b32_e32 v92, 0, v92, vcc
	v_cmp_le_i32_e32 vcc, v16, v218
	v_or_b32_e32 v16, 24, v237
	v_cvt_pk_bf16_f32 v82, v82, v83
	v_cvt_pk_bf16_f32 v83, v84, v85
	v_cvt_pk_bf16_f32 v84, v86, v87
	v_cvt_pk_bf16_f32 v85, v88, v89
	v_add_f32_e32 v221, v87, v221
	v_cndmask_b32_e32 v93, 0, v93, vcc
	v_cmp_le_i32_e32 vcc, v16, v218
	v_or_b32_e32 v16, 25, v237
	v_mfma_f32_32x32x16_bf16 v[66:81], v[146:149], v[82:85], 0
	v_add_f32_e32 v221, v88, v221
	v_cndmask_b32_e32 v94, 0, v94, vcc
	v_exp_f32_e32 v86, v96
	v_cmp_le_i32_e32 vcc, v16, v218
	v_or_b32_e32 v88, 26, v237
	v_add_f32_e32 v221, v89, v221
	v_cndmask_b32_e32 v87, 0, v95, vcc
	v_mfma_f32_32x32x16_bf16 v[50:65], v[142:145], v[82:85], 0
	v_cmp_le_i32_e32 vcc, v88, v218
	v_exp_f32_e32 v88, v97
	v_or_b32_e32 v82, 27, v237
	v_cndmask_b32_e32 v86, 0, v86, vcc
	v_cmp_le_i32_e32 vcc, v82, v218
	v_cvt_pk_bf16_f32 v82, v90, v91
	v_cvt_pk_bf16_f32 v83, v92, v93
	v_cndmask_b32_e32 v88, 0, v88, vcc
	v_cvt_pk_bf16_f32 v84, v94, v87
	v_cvt_pk_bf16_f32 v85, v86, v88
	v_add_f32_e32 v221, v90, v221
	v_add_f32_e32 v89, v91, v221
	v_mfma_f32_32x32x16_bf16 v[66:81], v[126:129], v[82:85], v[66:81]
	v_add_f32_e32 v89, v92, v89
	v_add_f32_e32 v89, v93, v89
	v_add_f32_e32 v89, v94, v89
	v_add_f32_e32 v87, v87, v89
	v_add_f32_e32 v86, v86, v87
	v_add_f32_e32 v221, v88, v86
	v_mfma_f32_32x32x16_bf16 v[50:65], v[114:117], v[82:85], v[50:65]
	s_cmp_lg_u32 s85, s86
	s_cbranch_scc1 .Lq_nl0_k0p1
	s_min_u32 s14, s87, 63
	s_nop 3
	v_readlane_b32 s30, v33, s14
	s_and_b32 s30, s30, 0xff
	s_lshl_b32 s30, s30, 13
	s_or_b32 s30, s30, 0x1000
	s_add_u32 s64, s11, s30
	s_addc_u32 s65, s12, 0
	s_add_u32 s66, s8, s30
	s_addc_u32 s67, s9, 0
	global_load_dwordx4 v[178:181], v2, s[64:65]
	global_load_dwordx4 v[174:177], v2, s[64:65] offset:1024
	global_load_dwordx4 v[170:173], v2, s[64:65] offset:2048
	global_load_dwordx4 v[166:169], v2, s[64:65] offset:3072
	global_load_dwordx4 v[146:149], v2, s[66:67]
	global_load_dwordx4 v[142:145], v2, s[66:67] offset:1024
	global_load_dwordx4 v[126:129], v2, s[66:67] offset:2048
	global_load_dwordx4 v[114:117], v2, s[66:67] offset:3072
	s_waitcnt vmcnt(20)
	s_branch .Lq_nl0d_k0p1

.Lq_wd_k1p0:
	v_bfe_u32 v28, s57, v18, 6
	v_lshl_add_u32 v218, s99, 6, v28
	v_mad_u32_u24 v21, v28, s82, v19
	v_mad_u32_u24 v32, v28, s82, v31
	v_and_b32_e32 v29, s18, v23
	v_cmp_ne_u32_e64 s[54:55], 0, v29
	s_and_b64 s[54:55], s[54:55], s[94:95]
	s_min_u32 s14, s85, 63
	s_nop 3
	v_readlane_b32 s30, v26, s14
	v_readlane_b32 s31, v27, s14
	s_nop 1
	v_bfe_u32 v28, s31, v18, 6
	v_lshl_add_u32 v29, s99, 6, v28
	v_mad_u32_u24 v29, v29, s47, v20
	global_load_dwordx4 v[238:241], v29, s[20:21]
	global_load_dwordx4 v[242:245], v29, s[20:21] offset:32
	global_load_dwordx4 v[246:249], v29, s[20:21] offset:64
	global_load_dwordx4 v[250:253], v29, s[20:21] offset:96
	s_lshl_b32 s0, s100, 6
	v_or_b32_e32 v237, s0, v206
	v_mov_b32_e32 v221, 0
	s_cmp_lg_u32 s100, s99
	s_cbranch_scc1 .Lq_s0n_k1p0
	v_and_b32_e32 v82, s18, v23
	v_cmp_ne_u32_e32 vcc, 0, v82
	s_and_b64 vcc, s[94:95], vcc
	v_mov_b32 v83, 0
	v_or_b32_e32 v16, 2, v237
	v_cndmask_b32_e32 v82, v236, v222, vcc
	v_sub_f32_e32 v82, v83, v82
	v_mov_b32_e32 v83, v82
	v_mov_b32_e32 v84, v82
	v_mov_b32_e32 v85, v82
	v_mov_b32_e32 v86, v82
	v_mov_b32_e32 v87, v82
	v_mov_b32_e32 v88, v82
	v_mov_b32_e32 v89, v82
	v_mov_b32_e32 v90, v82
	v_mov_b32_e32 v91, v82
	v_mov_b32_e32 v92, v82
	v_mov_b32_e32 v93, v82
	v_mov_b32_e32 v94, v82
	v_mov_b32_e32 v95, v82
	v_mov_b32_e32 v96, v82
	v_mov_b32_e32 v97, v82
	v_cmp_le_i32_e32 vcc, v237, v218
	v_or_b32_e32 v17, 3, v237
	v_mfma_f32_32x32x16_bf16 v[82:97], v[194:197], v[4:7], v[82:97]
	v_or_b32_e32 v30, 8, v237
	v_mfma_f32_32x32x16_bf16 v[82:97], v[190:193], v[8:11], v[82:97]
	v_mfma_f32_32x32x16_bf16 v[82:97], v[186:189], v[12:15], v[82:97]
	v_mfma_f32_32x32x16_bf16 v[82:97], v[182:185], v[98:101], v[82:97]
	s_nop 11
	v_exp_f32_e32 v82, v82
	v_exp_f32_e32 v83, v83
	v_exp_f32_e32 v84, v84
	v_exp_f32_e32 v85, v85
	v_exp_f32_e32 v86, v86
	v_cndmask_b32_e32 v82, 0, v82, vcc
	v_cmp_lt_i32_e32 vcc, v237, v218
	v_exp_f32_e32 v87, v87
	v_exp_f32_e32 v88, v88
	v_cndmask_b32_e32 v83, 0, v83, vcc
	v_cmp_le_i32_e32 vcc, v16, v218
	v_or_b32_e32 v16, 9, v237
	v_exp_f32_e32 v89, v89
	v_cndmask_b32_e32 v84, 0, v84, vcc
	v_cmp_le_i32_e32 vcc, v17, v218
	v_exp_f32_e32 v90, v90
	v_exp_f32_e32 v91, v91
	v_cndmask_b32_e32 v85, 0, v85, vcc
	v_cmp_le_i32_e32 vcc, v30, v218
	v_add_f32_e32 v221, v221, v82
	v_exp_f32_e32 v92, v92
	v_cndmask_b32_e32 v86, 0, v86, vcc
	v_cmp_le_i32_e32 vcc, v16, v218
	v_or_b32_e32 v16, 10, v237
	v_add_f32_e32 v221, v83, v221
	v_cndmask_b32_e32 v87, 0, v87, vcc
	v_cmp_le_i32_e32 vcc, v16, v218
	v_or_b32_e32 v16, 11, v237
	v_exp_f32_e32 v93, v93
	v_cndmask_b32_e32 v88, 0, v88, vcc
	v_cmp_le_i32_e32 vcc, v16, v218
	v_or_b32_e32 v16, 16, v237
	v_add_f32_e32 v221, v84, v221
	v_cndmask_b32_e32 v89, 0, v89, vcc
	v_cmp_le_i32_e32 vcc, v16, v218
	v_or_b32_e32 v16, 17, v237
	v_exp_f32_e32 v94, v94
	v_cndmask_b32_e32 v90, 0, v90, vcc
	v_cmp_le_i32_e32 vcc, v16, v218
	v_or_b32_e32 v16, 18, v237
	v_add_f32_e32 v221, v85, v221
	v_cndmask_b32_e32 v91, 0, v91, vcc
	v_cmp_le_i32_e32 vcc, v16, v218
	v_or_b32_e32 v16, 19, v237
	v_exp_f32_e32 v95, v95
	v_add_f32_e32 v221, v86, v221
	v_cndmask_b32_e32 v92, 0, v92, vcc
	v_cmp_le_i32_e32 vcc, v16, v218
	v_or_b32_e32 v16, 24, v237
	v_cvt_pk_bf16_f32 v82, v82, v83
	v_cvt_pk_bf16_f32 v83, v84, v85
	v_cvt_pk_bf16_f32 v84, v86, v87
	v_cvt_pk_bf16_f32 v85, v88, v89
	v_add_f32_e32 v221, v87, v221
	v_cndmask_b32_e32 v93, 0, v93, vcc
	v_cmp_le_i32_e32 vcc, v16, v218
	v_or_b32_e32 v16, 25, v237
	v_mfma_f32_32x32x16_bf16 v[66:81], v[134:137], v[82:85], 0
	v_add_f32_e32 v221, v88, v221
	v_cndmask_b32_e32 v94, 0, v94, vcc
	v_exp_f32_e32 v86, v96
	v_cmp_le_i32_e32 vcc, v16, v218
	v_or_b32_e32 v88, 26, v237
	v_add_f32_e32 v221, v89, v221
	v_cndmask_b32_e32 v87, 0, v95, vcc
	v_mfma_f32_32x32x16_bf16 v[50:65], v[130:133], v[82:85], 0
	v_cmp_le_i32_e32 vcc, v88, v218
	v_exp_f32_e32 v88, v97
	v_or_b32_e32 v82, 27, v237
	v_cndmask_b32_e32 v86, 0, v86, vcc
	v_cmp_le_i32_e32 vcc, v82, v218
	v_cvt_pk_bf16_f32 v82, v90, v91
	v_cvt_pk_bf16_f32 v83, v92, v93
	v_cndmask_b32_e32 v88, 0, v88, vcc
	v_cvt_pk_bf16_f32 v84, v94, v87
	v_cvt_pk_bf16_f32 v85, v86, v88
	v_add_f32_e32 v221, v90, v221
	v_add_f32_e32 v89, v91, v221
	v_mfma_f32_32x32x16_bf16 v[66:81], v[118:121], v[82:85], v[66:81]
	v_add_f32_e32 v89, v92, v89
	v_add_f32_e32 v89, v93, v89
	v_add_f32_e32 v89, v94, v89
	v_add_f32_e32 v87, v87, v89
	v_add_f32_e32 v86, v86, v87
	v_add_f32_e32 v221, v88, v86
	v_mfma_f32_32x32x16_bf16 v[50:65], v[102:105], v[82:85], v[50:65]
	s_cmp_lg_u32 s85, s86
	s_cbranch_scc1 .Lq_nl0_k1p0
	s_min_u32 s14, s87, 63
	s_nop 3
	v_readlane_b32 s30, v33, s14
	s_and_b32 s30, s30, 0xff
	s_lshl_b32 s30, s30, 13
	s_or_b32 s30, s30, 0x1000
	s_add_u32 s64, s11, s30
	s_addc_u32 s65, s12, 0
	s_add_u32 s66, s8, s30
	s_addc_u32 s67, s9, 0
	global_load_dwordx4 v[194:197], v2, s[64:65]
	global_load_dwordx4 v[190:193], v2, s[64:65] offset:1024
	global_load_dwordx4 v[186:189], v2, s[64:65] offset:2048
	global_load_dwordx4 v[182:185], v2, s[64:65] offset:3072
	global_load_dwordx4 v[134:137], v2, s[66:67]
	global_load_dwordx4 v[130:133], v2, s[66:67] offset:1024
	global_load_dwordx4 v[118:121], v2, s[66:67] offset:2048
	global_load_dwordx4 v[102:105], v2, s[66:67] offset:3072
	s_waitcnt vmcnt(20)
	s_branch .Lq_nl0d_k1p0

.Lq_wd_k1p1:
	v_bfe_u32 v28, s57, v18, 6
	v_lshl_add_u32 v218, s99, 6, v28
	v_mad_u32_u24 v21, v28, s82, v19
	v_mad_u32_u24 v32, v28, s82, v31
	v_and_b32_e32 v29, s18, v23
	v_cmp_ne_u32_e64 s[54:55], 0, v29
	s_and_b64 s[54:55], s[54:55], s[94:95]
	s_min_u32 s14, s85, 63
	s_nop 3
	v_readlane_b32 s30, v26, s14
	v_readlane_b32 s31, v27, s14
	s_nop 1
	v_bfe_u32 v28, s31, v18, 6
	v_lshl_add_u32 v29, s99, 6, v28
	v_mad_u32_u24 v29, v29, s47, v20
	global_load_dwordx4 v[4:7], v29, s[20:21]
	global_load_dwordx4 v[8:11], v29, s[20:21] offset:32
	global_load_dwordx4 v[12:15], v29, s[20:21] offset:64
	global_load_dwordx4 v[98:101], v29, s[20:21] offset:96
	s_lshl_b32 s0, s100, 6
	v_or_b32_e32 v237, s0, v206
	v_mov_b32_e32 v221, 0
	s_cmp_lg_u32 s100, s99
	s_cbranch_scc1 .Lq_s0n_k1p1
	v_and_b32_e32 v82, s18, v23
	v_cmp_ne_u32_e32 vcc, 0, v82
	s_and_b64 vcc, s[94:95], vcc
	v_mov_b32 v83, 0
	v_or_b32_e32 v16, 2, v237
	v_cndmask_b32_e32 v82, v236, v222, vcc
	v_sub_f32_e32 v82, v83, v82
	v_mov_b32_e32 v83, v82
	v_mov_b32_e32 v84, v82
	v_mov_b32_e32 v85, v82
	v_mov_b32_e32 v86, v82
	v_mov_b32_e32 v87, v82
	v_mov_b32_e32 v88, v82
	v_mov_b32_e32 v89, v82
	v_mov_b32_e32 v90, v82
	v_mov_b32_e32 v91, v82
	v_mov_b32_e32 v92, v82
	v_mov_b32_e32 v93, v82
	v_mov_b32_e32 v94, v82
	v_mov_b32_e32 v95, v82
	v_mov_b32_e32 v96, v82
	v_mov_b32_e32 v97, v82
	v_cmp_le_i32_e32 vcc, v237, v218
	v_or_b32_e32 v17, 3, v237
	v_mfma_f32_32x32x16_bf16 v[82:97], v[194:197], v[238:241], v[82:97]
	v_or_b32_e32 v30, 8, v237
	v_mfma_f32_32x32x16_bf16 v[82:97], v[190:193], v[242:245], v[82:97]
	v_mfma_f32_32x32x16_bf16 v[82:97], v[186:189], v[246:249], v[82:97]
	v_mfma_f32_32x32x16_bf16 v[82:97], v[182:185], v[250:253], v[82:97]
	s_nop 11
	v_exp_f32_e32 v82, v82
	v_exp_f32_e32 v83, v83
	v_exp_f32_e32 v84, v84
	v_exp_f32_e32 v85, v85
	v_exp_f32_e32 v86, v86
	v_cndmask_b32_e32 v82, 0, v82, vcc
	v_cmp_lt_i32_e32 vcc, v237, v218
	v_exp_f32_e32 v87, v87
	v_exp_f32_e32 v88, v88
	v_cndmask_b32_e32 v83, 0, v83, vcc
	v_cmp_le_i32_e32 vcc, v16, v218
	v_or_b32_e32 v16, 9, v237
	v_exp_f32_e32 v89, v89
	v_cndmask_b32_e32 v84, 0, v84, vcc
	v_cmp_le_i32_e32 vcc, v17, v218
	v_exp_f32_e32 v90, v90
	v_exp_f32_e32 v91, v91
	v_cndmask_b32_e32 v85, 0, v85, vcc
	v_cmp_le_i32_e32 vcc, v30, v218
	v_add_f32_e32 v221, v221, v82
	v_exp_f32_e32 v92, v92
	v_cndmask_b32_e32 v86, 0, v86, vcc
	v_cmp_le_i32_e32 vcc, v16, v218
	v_or_b32_e32 v16, 10, v237
	v_add_f32_e32 v221, v83, v221
	v_cndmask_b32_e32 v87, 0, v87, vcc
	v_cmp_le_i32_e32 vcc, v16, v218
	v_or_b32_e32 v16, 11, v237
	v_exp_f32_e32 v93, v93
	v_cndmask_b32_e32 v88, 0, v88, vcc
	v_cmp_le_i32_e32 vcc, v16, v218
	v_or_b32_e32 v16, 16, v237
	v_add_f32_e32 v221, v84, v221
	v_cndmask_b32_e32 v89, 0, v89, vcc
	v_cmp_le_i32_e32 vcc, v16, v218
	v_or_b32_e32 v16, 17, v237
	v_exp_f32_e32 v94, v94
	v_cndmask_b32_e32 v90, 0, v90, vcc
	v_cmp_le_i32_e32 vcc, v16, v218
	v_or_b32_e32 v16, 18, v237
	v_add_f32_e32 v221, v85, v221
	v_cndmask_b32_e32 v91, 0, v91, vcc
	v_cmp_le_i32_e32 vcc, v16, v218
	v_or_b32_e32 v16, 19, v237
	v_exp_f32_e32 v95, v95
	v_add_f32_e32 v221, v86, v221
	v_cndmask_b32_e32 v92, 0, v92, vcc
	v_cmp_le_i32_e32 vcc, v16, v218
	v_or_b32_e32 v16, 24, v237
	v_cvt_pk_bf16_f32 v82, v82, v83
	v_cvt_pk_bf16_f32 v83, v84, v85
	v_cvt_pk_bf16_f32 v84, v86, v87
	v_cvt_pk_bf16_f32 v85, v88, v89
	v_add_f32_e32 v221, v87, v221
	v_cndmask_b32_e32 v93, 0, v93, vcc
	v_cmp_le_i32_e32 vcc, v16, v218
	v_or_b32_e32 v16, 25, v237
	v_mfma_f32_32x32x16_bf16 v[66:81], v[134:137], v[82:85], 0
	v_add_f32_e32 v221, v88, v221
	v_cndmask_b32_e32 v94, 0, v94, vcc
	v_exp_f32_e32 v86, v96
	v_cmp_le_i32_e32 vcc, v16, v218
	v_or_b32_e32 v88, 26, v237
	v_add_f32_e32 v221, v89, v221
	v_cndmask_b32_e32 v87, 0, v95, vcc
	v_mfma_f32_32x32x16_bf16 v[50:65], v[130:133], v[82:85], 0
	v_cmp_le_i32_e32 vcc, v88, v218
	v_exp_f32_e32 v88, v97
	v_or_b32_e32 v82, 27, v237
	v_cndmask_b32_e32 v86, 0, v86, vcc
	v_cmp_le_i32_e32 vcc, v82, v218
	v_cvt_pk_bf16_f32 v82, v90, v91
	v_cvt_pk_bf16_f32 v83, v92, v93
	v_cndmask_b32_e32 v88, 0, v88, vcc
	v_cvt_pk_bf16_f32 v84, v94, v87
	v_cvt_pk_bf16_f32 v85, v86, v88
	v_add_f32_e32 v221, v90, v221
	v_add_f32_e32 v89, v91, v221
	v_mfma_f32_32x32x16_bf16 v[66:81], v[118:121], v[82:85], v[66:81]
	v_add_f32_e32 v89, v92, v89
	v_add_f32_e32 v89, v93, v89
	v_add_f32_e32 v89, v94, v89
	v_add_f32_e32 v87, v87, v89
	v_add_f32_e32 v86, v86, v87
	v_add_f32_e32 v221, v88, v86
	v_mfma_f32_32x32x16_bf16 v[50:65], v[102:105], v[82:85], v[50:65]
	s_cmp_lg_u32 s85, s86
	s_cbranch_scc1 .Lq_nl0_k1p1
	s_min_u32 s14, s87, 63
	s_nop 3
	v_readlane_b32 s30, v33, s14
	s_and_b32 s30, s30, 0xff
	s_lshl_b32 s30, s30, 13
	s_or_b32 s30, s30, 0x1000
	s_add_u32 s64, s11, s30
	s_addc_u32 s65, s12, 0
	s_add_u32 s66, s8, s30
	s_addc_u32 s67, s9, 0
	global_load_dwordx4 v[194:197], v2, s[64:65]
	global_load_dwordx4 v[190:193], v2, s[64:65] offset:1024
	global_load_dwordx4 v[186:189], v2, s[64:65] offset:2048
	global_load_dwordx4 v[182:185], v2, s[64:65] offset:3072
	global_load_dwordx4 v[134:137], v2, s[66:67]
	global_load_dwordx4 v[130:133], v2, s[66:67] offset:1024
	global_load_dwordx4 v[118:121], v2, s[66:67] offset:2048
	global_load_dwordx4 v[102:105], v2, s[66:67] offset:3072
	s_waitcnt vmcnt(20)
	s_branch .Lq_nl0d_k1p1

.Lq_wd_k2p0:
	v_bfe_u32 v28, s57, v18, 6
	v_lshl_add_u32 v218, s99, 6, v28
	v_mad_u32_u24 v21, v28, s82, v19
	v_mad_u32_u24 v32, v28, s82, v31
	v_and_b32_e32 v29, s18, v23
	v_cmp_ne_u32_e64 s[54:55], 0, v29
	s_and_b64 s[54:55], s[54:55], s[94:95]
	s_min_u32 s14, s85, 63
	s_nop 3
	v_readlane_b32 s30, v26, s14
	v_readlane_b32 s31, v27, s14
	s_nop 1
	v_bfe_u32 v28, s31, v18, 6
	v_lshl_add_u32 v29, s99, 6, v28
	v_mad_u32_u24 v29, v29, s47, v20
	global_load_dwordx4 v[238:241], v29, s[20:21]
	global_load_dwordx4 v[242:245], v29, s[20:21] offset:32
	global_load_dwordx4 v[246:249], v29, s[20:21] offset:64
	global_load_dwordx4 v[250:253], v29, s[20:21] offset:96
	s_lshl_b32 s0, s100, 6
	v_or_b32_e32 v237, s0, v206
	v_mov_b32_e32 v221, 0
	s_cmp_lg_u32 s100, s99
	s_cbranch_scc1 .Lq_s0n_k2p0
	v_and_b32_e32 v82, s18, v23
	v_cmp_ne_u32_e32 vcc, 0, v82
	s_and_b64 vcc, s[94:95], vcc
	v_mov_b32 v83, 0
	v_or_b32_e32 v16, 2, v237
	v_cndmask_b32_e32 v82, v236, v222, vcc
	v_sub_f32_e32 v82, v83, v82
	v_mov_b32_e32 v83, v82
	v_mov_b32_e32 v84, v82
	v_mov_b32_e32 v85, v82
	v_mov_b32_e32 v86, v82
	v_mov_b32_e32 v87, v82
	v_mov_b32_e32 v88, v82
	v_mov_b32_e32 v89, v82
	v_mov_b32_e32 v90, v82
	v_mov_b32_e32 v91, v82
	v_mov_b32_e32 v92, v82
	v_mov_b32_e32 v93, v82
	v_mov_b32_e32 v94, v82
	v_mov_b32_e32 v95, v82
	v_mov_b32_e32 v96, v82
	v_mov_b32_e32 v97, v82
	v_cmp_le_i32_e32 vcc, v237, v218
	v_or_b32_e32 v17, 3, v237
	v_mfma_f32_32x32x16_bf16 v[82:97], v[162:165], v[4:7], v[82:97]
	v_or_b32_e32 v30, 8, v237
	v_mfma_f32_32x32x16_bf16 v[82:97], v[154:157], v[8:11], v[82:97]
	v_mfma_f32_32x32x16_bf16 v[82:97], v[150:153], v[12:15], v[82:97]
	v_mfma_f32_32x32x16_bf16 v[82:97], v[158:161], v[98:101], v[82:97]
	s_nop 11
	v_exp_f32_e32 v82, v82
	v_exp_f32_e32 v83, v83
	v_exp_f32_e32 v84, v84
	v_exp_f32_e32 v85, v85
	v_exp_f32_e32 v86, v86
	v_cndmask_b32_e32 v82, 0, v82, vcc
	v_cmp_lt_i32_e32 vcc, v237, v218
	v_exp_f32_e32 v87, v87
	v_exp_f32_e32 v88, v88
	v_cndmask_b32_e32 v83, 0, v83, vcc
	v_cmp_le_i32_e32 vcc, v16, v218
	v_or_b32_e32 v16, 9, v237
	v_exp_f32_e32 v89, v89
	v_cndmask_b32_e32 v84, 0, v84, vcc
	v_cmp_le_i32_e32 vcc, v17, v218
	v_exp_f32_e32 v90, v90
	v_exp_f32_e32 v91, v91
	v_cndmask_b32_e32 v85, 0, v85, vcc
	v_cmp_le_i32_e32 vcc, v30, v218
	v_add_f32_e32 v221, v221, v82
	v_exp_f32_e32 v92, v92
	v_cndmask_b32_e32 v86, 0, v86, vcc
	v_cmp_le_i32_e32 vcc, v16, v218
	v_or_b32_e32 v16, 10, v237
	v_add_f32_e32 v221, v83, v221
	v_cndmask_b32_e32 v87, 0, v87, vcc
	v_cmp_le_i32_e32 vcc, v16, v218
	v_or_b32_e32 v16, 11, v237
	v_exp_f32_e32 v93, v93
	v_cndmask_b32_e32 v88, 0, v88, vcc
	v_cmp_le_i32_e32 vcc, v16, v218
	v_or_b32_e32 v16, 16, v237
	v_add_f32_e32 v221, v84, v221
	v_cndmask_b32_e32 v89, 0, v89, vcc
	v_cmp_le_i32_e32 vcc, v16, v218
	v_or_b32_e32 v16, 17, v237
	v_exp_f32_e32 v94, v94
	v_cndmask_b32_e32 v90, 0, v90, vcc
	v_cmp_le_i32_e32 vcc, v16, v218
	v_or_b32_e32 v16, 18, v237
	v_add_f32_e32 v221, v85, v221
	v_cndmask_b32_e32 v91, 0, v91, vcc
	v_cmp_le_i32_e32 vcc, v16, v218
	v_or_b32_e32 v16, 19, v237
	v_exp_f32_e32 v95, v95
	v_add_f32_e32 v221, v86, v221
	v_cndmask_b32_e32 v92, 0, v92, vcc
	v_cmp_le_i32_e32 vcc, v16, v218
	v_or_b32_e32 v16, 24, v237
	v_cvt_pk_bf16_f32 v82, v82, v83
	v_cvt_pk_bf16_f32 v83, v84, v85
	v_cvt_pk_bf16_f32 v84, v86, v87
	v_cvt_pk_bf16_f32 v85, v88, v89
	v_add_f32_e32 v221, v87, v221
	v_cndmask_b32_e32 v93, 0, v93, vcc
	v_cmp_le_i32_e32 vcc, v16, v218
	v_or_b32_e32 v16, 25, v237
	v_mfma_f32_32x32x16_bf16 v[66:81], v[138:141], v[82:85], 0
	v_add_f32_e32 v221, v88, v221
	v_cndmask_b32_e32 v94, 0, v94, vcc
	v_exp_f32_e32 v86, v96
	v_cmp_le_i32_e32 vcc, v16, v218
	v_or_b32_e32 v88, 26, v237
	v_add_f32_e32 v221, v89, v221
	v_cndmask_b32_e32 v87, 0, v95, vcc
	v_mfma_f32_32x32x16_bf16 v[50:65], v[122:125], v[82:85], 0
	v_cmp_le_i32_e32 vcc, v88, v218
	v_exp_f32_e32 v88, v97
	v_or_b32_e32 v82, 27, v237
	v_cndmask_b32_e32 v86, 0, v86, vcc
	v_cmp_le_i32_e32 vcc, v82, v218
	v_cvt_pk_bf16_f32 v82, v90, v91
	v_cvt_pk_bf16_f32 v83, v92, v93
	v_cndmask_b32_e32 v88, 0, v88, vcc
	v_cvt_pk_bf16_f32 v84, v94, v87
	v_cvt_pk_bf16_f32 v85, v86, v88
	v_add_f32_e32 v221, v90, v221
	v_add_f32_e32 v89, v91, v221
	v_mfma_f32_32x32x16_bf16 v[66:81], v[110:113], v[82:85], v[66:81]
	v_add_f32_e32 v89, v92, v89
	v_add_f32_e32 v89, v93, v89
	v_add_f32_e32 v89, v94, v89
	v_add_f32_e32 v87, v87, v89
	v_add_f32_e32 v86, v86, v87
	v_add_f32_e32 v221, v88, v86
	v_mfma_f32_32x32x16_bf16 v[50:65], v[106:109], v[82:85], v[50:65]
	s_cmp_lg_u32 s85, s86
	s_cbranch_scc1 .Lq_nl0_k2p0
	s_min_u32 s14, s87, 63
	s_nop 3
	v_readlane_b32 s30, v33, s14
	s_and_b32 s30, s30, 0xff
	s_lshl_b32 s30, s30, 13
	s_or_b32 s30, s30, 0x1000
	s_add_u32 s64, s11, s30
	s_addc_u32 s65, s12, 0
	s_add_u32 s66, s8, s30
	s_addc_u32 s67, s9, 0
	global_load_dwordx4 v[162:165], v2, s[64:65]
	global_load_dwordx4 v[154:157], v2, s[64:65] offset:1024
	global_load_dwordx4 v[150:153], v2, s[64:65] offset:2048
	global_load_dwordx4 v[158:161], v2, s[64:65] offset:3072
	global_load_dwordx4 v[138:141], v2, s[66:67]
	global_load_dwordx4 v[122:125], v2, s[66:67] offset:1024
	global_load_dwordx4 v[110:113], v2, s[66:67] offset:2048
	global_load_dwordx4 v[106:109], v2, s[66:67] offset:3072
	s_waitcnt vmcnt(20)
	s_branch .Lq_nl0d_k2p0

.Lq_wd_k2p1:
	v_bfe_u32 v28, s57, v18, 6
	v_lshl_add_u32 v218, s99, 6, v28
	v_mad_u32_u24 v21, v28, s82, v19
	v_mad_u32_u24 v32, v28, s82, v31
	v_and_b32_e32 v29, s18, v23
	v_cmp_ne_u32_e64 s[54:55], 0, v29
	s_and_b64 s[54:55], s[54:55], s[94:95]
	s_min_u32 s14, s85, 63
	s_nop 3
	v_readlane_b32 s30, v26, s14
	v_readlane_b32 s31, v27, s14
	s_nop 1
	v_bfe_u32 v28, s31, v18, 6
	v_lshl_add_u32 v29, s99, 6, v28
	v_mad_u32_u24 v29, v29, s47, v20
	global_load_dwordx4 v[4:7], v29, s[20:21]
	global_load_dwordx4 v[8:11], v29, s[20:21] offset:32
	global_load_dwordx4 v[12:15], v29, s[20:21] offset:64
	global_load_dwordx4 v[98:101], v29, s[20:21] offset:96
	s_lshl_b32 s0, s100, 6
	v_or_b32_e32 v237, s0, v206
	v_mov_b32_e32 v221, 0
	s_cmp_lg_u32 s100, s99
	s_cbranch_scc1 .Lq_s0n_k2p1
	v_and_b32_e32 v82, s18, v23
	v_cmp_ne_u32_e32 vcc, 0, v82
	s_and_b64 vcc, s[94:95], vcc
	v_mov_b32 v83, 0
	v_or_b32_e32 v16, 2, v237
	v_cndmask_b32_e32 v82, v236, v222, vcc
	v_sub_f32_e32 v82, v83, v82
	v_mov_b32_e32 v83, v82
	v_mov_b32_e32 v84, v82
	v_mov_b32_e32 v85, v82
	v_mov_b32_e32 v86, v82
	v_mov_b32_e32 v87, v82
	v_mov_b32_e32 v88, v82
	v_mov_b32_e32 v89, v82
	v_mov_b32_e32 v90, v82
	v_mov_b32_e32 v91, v82
	v_mov_b32_e32 v92, v82
	v_mov_b32_e32 v93, v82
	v_mov_b32_e32 v94, v82
	v_mov_b32_e32 v95, v82
	v_mov_b32_e32 v96, v82
	v_mov_b32_e32 v97, v82
	v_cmp_le_i32_e32 vcc, v237, v218
	v_or_b32_e32 v17, 3, v237
	v_mfma_f32_32x32x16_bf16 v[82:97], v[162:165], v[238:241], v[82:97]
	v_or_b32_e32 v30, 8, v237
	v_mfma_f32_32x32x16_bf16 v[82:97], v[154:157], v[242:245], v[82:97]
	v_mfma_f32_32x32x16_bf16 v[82:97], v[150:153], v[246:249], v[82:97]
	v_mfma_f32_32x32x16_bf16 v[82:97], v[158:161], v[250:253], v[82:97]
	s_nop 11
	v_exp_f32_e32 v82, v82
	v_exp_f32_e32 v83, v83
	v_exp_f32_e32 v84, v84
	v_exp_f32_e32 v85, v85
	v_exp_f32_e32 v86, v86
	v_cndmask_b32_e32 v82, 0, v82, vcc
	v_cmp_lt_i32_e32 vcc, v237, v218
	v_exp_f32_e32 v87, v87
	v_exp_f32_e32 v88, v88
	v_cndmask_b32_e32 v83, 0, v83, vcc
	v_cmp_le_i32_e32 vcc, v16, v218
	v_or_b32_e32 v16, 9, v237
	v_exp_f32_e32 v89, v89
	v_cndmask_b32_e32 v84, 0, v84, vcc
	v_cmp_le_i32_e32 vcc, v17, v218
	v_exp_f32_e32 v90, v90
	v_exp_f32_e32 v91, v91
	v_cndmask_b32_e32 v85, 0, v85, vcc
	v_cmp_le_i32_e32 vcc, v30, v218
	v_add_f32_e32 v221, v221, v82
	v_exp_f32_e32 v92, v92
	v_cndmask_b32_e32 v86, 0, v86, vcc
	v_cmp_le_i32_e32 vcc, v16, v218
	v_or_b32_e32 v16, 10, v237
	v_add_f32_e32 v221, v83, v221
	v_cndmask_b32_e32 v87, 0, v87, vcc
	v_cmp_le_i32_e32 vcc, v16, v218
	v_or_b32_e32 v16, 11, v237
	v_exp_f32_e32 v93, v93
	v_cndmask_b32_e32 v88, 0, v88, vcc
	v_cmp_le_i32_e32 vcc, v16, v218
	v_or_b32_e32 v16, 16, v237
	v_add_f32_e32 v221, v84, v221
	v_cndmask_b32_e32 v89, 0, v89, vcc
	v_cmp_le_i32_e32 vcc, v16, v218
	v_or_b32_e32 v16, 17, v237
	v_exp_f32_e32 v94, v94
	v_cndmask_b32_e32 v90, 0, v90, vcc
	v_cmp_le_i32_e32 vcc, v16, v218
	v_or_b32_e32 v16, 18, v237
	v_add_f32_e32 v221, v85, v221
	v_cndmask_b32_e32 v91, 0, v91, vcc
	v_cmp_le_i32_e32 vcc, v16, v218
	v_or_b32_e32 v16, 19, v237
	v_exp_f32_e32 v95, v95
	v_add_f32_e32 v221, v86, v221
	v_cndmask_b32_e32 v92, 0, v92, vcc
	v_cmp_le_i32_e32 vcc, v16, v218
	v_or_b32_e32 v16, 24, v237
	v_cvt_pk_bf16_f32 v82, v82, v83
	v_cvt_pk_bf16_f32 v83, v84, v85
	v_cvt_pk_bf16_f32 v84, v86, v87
	v_cvt_pk_bf16_f32 v85, v88, v89
	v_add_f32_e32 v221, v87, v221
	v_cndmask_b32_e32 v93, 0, v93, vcc
	v_cmp_le_i32_e32 vcc, v16, v218
	v_or_b32_e32 v16, 25, v237
	v_mfma_f32_32x32x16_bf16 v[66:81], v[138:141], v[82:85], 0
	v_add_f32_e32 v221, v88, v221
	v_cndmask_b32_e32 v94, 0, v94, vcc
	v_exp_f32_e32 v86, v96
	v_cmp_le_i32_e32 vcc, v16, v218
	v_or_b32_e32 v88, 26, v237
	v_add_f32_e32 v221, v89, v221
	v_cndmask_b32_e32 v87, 0, v95, vcc
	v_mfma_f32_32x32x16_bf16 v[50:65], v[122:125], v[82:85], 0
	v_cmp_le_i32_e32 vcc, v88, v218
	v_exp_f32_e32 v88, v97
	v_or_b32_e32 v82, 27, v237
	v_cndmask_b32_e32 v86, 0, v86, vcc
	v_cmp_le_i32_e32 vcc, v82, v218
	v_cvt_pk_bf16_f32 v82, v90, v91
	v_cvt_pk_bf16_f32 v83, v92, v93
	v_cndmask_b32_e32 v88, 0, v88, vcc
	v_cvt_pk_bf16_f32 v84, v94, v87
	v_cvt_pk_bf16_f32 v85, v86, v88
	v_add_f32_e32 v221, v90, v221
	v_add_f32_e32 v89, v91, v221
	v_mfma_f32_32x32x16_bf16 v[66:81], v[110:113], v[82:85], v[66:81]
	v_add_f32_e32 v89, v92, v89
	v_add_f32_e32 v89, v93, v89
	v_add_f32_e32 v89, v94, v89
	v_add_f32_e32 v87, v87, v89
	v_add_f32_e32 v86, v86, v87
	v_add_f32_e32 v221, v88, v86
	v_mfma_f32_32x32x16_bf16 v[50:65], v[106:109], v[82:85], v[50:65]
	s_cmp_lg_u32 s85, s86
	s_cbranch_scc1 .Lq_nl0_k2p1
	s_min_u32 s14, s87, 63
	s_nop 3
	v_readlane_b32 s30, v33, s14
	s_and_b32 s30, s30, 0xff
	s_lshl_b32 s30, s30, 13
	s_or_b32 s30, s30, 0x1000
	s_add_u32 s64, s11, s30
	s_addc_u32 s65, s12, 0
	s_add_u32 s66, s8, s30
	s_addc_u32 s67, s9, 0
	global_load_dwordx4 v[162:165], v2, s[64:65]
	global_load_dwordx4 v[154:157], v2, s[64:65] offset:1024
	global_load_dwordx4 v[150:153], v2, s[64:65] offset:2048
	global_load_dwordx4 v[158:161], v2, s[64:65] offset:3072
	global_load_dwordx4 v[138:141], v2, s[66:67]
	global_load_dwordx4 v[122:125], v2, s[66:67] offset:1024
	global_load_dwordx4 v[110:113], v2, s[66:67] offset:2048
	global_load_dwordx4 v[106:109], v2, s[66:67] offset:3072
	s_waitcnt vmcnt(20)
	s_branch .Lq_nl0d_k2p1
